# MLA loop: in the second tile of each barrier interval the LDS store / reload pieces are issued one MFMA slot earlier (slots 13-15), keeping the slots nearest the barrier lighter
# speedup vs baseline: 1.0044x; 1.0014x over previous
; template <int VAR>
; __device__ __forceinline__ void attn_phase(LAS unsigned char* lds, const AttnP P, int vcu, int G, int wave_s) {
;     ...
;                 if (ND0 == 6) {
;                     KR1(0); KR1(1); KR1(2); KR1(3); SB();
;                     QK1(0, negm); EX2(pc0, 0, w0.x); KR1(4); SB();
;                     QK1(1, negm); EX2(pc0, 2, w0.y); KR1(5); SB();
;                     QK1(2, pn0); EX2(pc0, 4, w0.z); KR1(6); SB();
;                     QK1(3, pn1); EX2(pc0, 6, w0.w); KR1(7); SB();
;                     QK1(4, pn0); EX2(pc0, 8, w1.x); KR1(8); SB();
;                     QK1(5, pn1); EX2(pc0, 10, w1.y); KR1(9); SB();
;                     QK1(6, pn0); EX2(pc0, 12, w1.z); KR1(10); SB();
;                     QK1(7, pn1); EX2(pc0, 14, w1.w); KR1(11); SB();
;                     QK1(8, pn0); EX2(pc1, 0, w2.x); VR1(0); SB();
;                     QK1(9, pn1); EX2(pc1, 2, w2.y); VR1(1); SB();
;                     QK1(10, pn0); EX2(pc1, 4, w2.z); VR1(2); SB();
;                     QK1(11, pn1); EX2(pc1, 6, w2.w); VR1(3); SB();
;                 } else {
;                     KR1(0); KR1(1); KR1(2); KR1(3); SB();
;                     QK1(0, negm); EX2(pc0, 0, w0.x); EX2(pc0, 2, w0.y); KR1(4); SB();
;                     QK1(1, negm); EX2(pc0, 4, w0.z); EX2(pc0, 6, w0.w); KR1(5); SB();
;                     QK1(2, pn0); EX2(pc0, 8, w1.x); EX2(pc0, 10, w1.y); KR1(6); SB();
;                     QK1(3, pn1); EX2(pc0, 12, w1.z); EX2(pc0, 14, w1.w); KR1(7); SB();
;                     QK1(4, pn0); EX2(pc1, 0, w2.x); VR1(0); SB();
;                     QK1(5, pn1); EX2(pc1, 2, w2.y); VR1(1); SB();
;                     QK1(6, pn0); EX2(pc1, 4, w2.z); VR1(2); SB();
;                     QK1(7, pn1); EX2(pc1, 6, w2.w); VR1(3); SB();
;                 }
;                 PV1(0, w0); EX2(pc1, 8, w3.x); VR1(4); SB();
;                 PV1(1, w0); EX2(pc1, 10, w3.y); VR1(5); SB();
;                 PV1(2, w1); EX2(pc1, 12, w3.z); VR1(6); SB();
;                 PV1(3, w1); EX2(pc1, 14, w3.w); VR1(7); SB();
;                 lrun += sacc;
;                 PV1(4, w2); MASK_TILE(pn0, pn1, t + 1); SB();
;                 PV1(5, w2); SB();
;                 PV1(6, w3); SB();
;                 PV1(7, w3); rmn = rowmax32(pn0, pn1); if (!USE_NEGM) rmn -= mref; SB();
;     ...
;             if (hn) { STOREK(t & 1); STOREV((t + 1) & 1); }
;             __syncthreads();
.Lmla_p1_go:
	v_exp_f32_e32 v222, v82
	v_exp_f32_e32 v223, v83
	v_add_f32_e32 v164, 0, v222
	v_cvt_pk_bf16_f32 v206, v222, v223
	v_add_f32_e32 v164, v223, v164
	v_exp_f32_e32 v224, v84
	v_exp_f32_e32 v225, v85
	v_add_f32_e32 v164, v224, v164
	v_cvt_pk_bf16_f32 v207, v224, v225
	v_add_f32_e32 v164, v225, v164
	s_waitcnt lgkmcnt(4)
	v_mfma_f32_32x32x16_bf16 v[34:49], v[182:185], v[114:117], v[66:81]
	ds_read_b128 v[198:201], v174 offset:45120
	v_exp_f32_e32 v222, v86
	v_exp_f32_e32 v223, v87
	v_add_f32_e32 v164, v222, v164
	v_cvt_pk_bf16_f32 v208, v222, v223
	v_add_f32_e32 v164, v223, v164
	s_waitcnt lgkmcnt(4)
	v_mfma_f32_32x32x16_bf16 v[50:65], v[186:189], v[114:117], v[66:81]
	ds_read_b128 v[182:185], v174 offset:51776
	v_exp_f32_e32 v224, v88
	v_exp_f32_e32 v225, v89
	v_add_f32_e32 v164, v224, v164
	v_cvt_pk_bf16_f32 v209, v224, v225
	v_add_f32_e32 v164, v225, v164
	s_waitcnt lgkmcnt(3)
	v_mfma_f32_32x32x16_bf16 v[34:49], v[190:193], v[118:121], v[34:49]
	ds_read_b128 v[186:189], v174 offset:45152
	v_exp_f32_e32 v222, v90
	v_exp_f32_e32 v223, v91
	v_add_f32_e32 v164, v222, v164
	v_cvt_pk_bf16_f32 v210, v222, v223
	v_add_f32_e32 v164, v223, v164
	s_waitcnt lgkmcnt(3)
	v_mfma_f32_32x32x16_bf16 v[50:65], v[194:197], v[118:121], v[50:65]
	ds_read_b128 v[190:193], v174 offset:51808
	v_exp_f32_e32 v224, v92
	v_exp_f32_e32 v225, v93
	v_add_f32_e32 v164, v224, v164
	v_cvt_pk_bf16_f32 v211, v224, v225
	v_add_f32_e32 v164, v225, v164
	s_waitcnt lgkmcnt(3)
	v_mfma_f32_32x32x16_bf16 v[34:49], v[198:201], v[122:125], v[34:49]
	ds_read_b128 v[194:197], v174 offset:45184
	v_exp_f32_e32 v222, v94
	v_exp_f32_e32 v223, v95
	v_add_f32_e32 v164, v222, v164
	v_cvt_pk_bf16_f32 v212, v222, v223
	v_add_f32_e32 v164, v223, v164
	s_waitcnt lgkmcnt(3)
	v_mfma_f32_32x32x16_bf16 v[50:65], v[182:185], v[122:125], v[50:65]
	ds_read_b128 v[198:201], v174 offset:51840
	v_exp_f32_e32 v224, v96
	v_exp_f32_e32 v225, v97
	v_add_f32_e32 v164, v224, v164
	v_cvt_pk_bf16_f32 v213, v224, v225
	v_add_f32_e32 v164, v225, v164
	s_waitcnt lgkmcnt(3)
	v_mfma_f32_32x32x16_bf16 v[34:49], v[186:189], v[126:129], v[34:49]
	ds_read_b128 v[182:185], v174 offset:45216
	v_exp_f32_e32 v222, v98
	v_exp_f32_e32 v223, v99
	v_add_f32_e32 v164, v222, v164
	v_cvt_pk_bf16_f32 v214, v222, v223
	v_add_f32_e32 v164, v223, v164
	s_waitcnt lgkmcnt(3)
	v_mfma_f32_32x32x16_bf16 v[50:65], v[190:193], v[126:129], v[50:65]
	ds_read_b128 v[186:189], v174 offset:51872
	v_exp_f32_e32 v224, v100
	v_exp_f32_e32 v225, v101
	v_add_f32_e32 v164, v224, v164
	v_cvt_pk_bf16_f32 v215, v224, v225
	v_add_f32_e32 v164, v225, v164
	s_waitcnt lgkmcnt(3)
	v_mfma_f32_32x32x16_bf16 v[34:49], v[194:197], v[130:133], v[34:49]
	ds_read_b128 v[190:193], v228 offset:35840
	v_exp_f32_e32 v222, v102
	v_exp_f32_e32 v223, v103
	v_add_f32_e32 v164, v222, v164
	v_cvt_pk_bf16_f32 v216, v222, v223
	v_add_f32_e32 v164, v223, v164
	s_waitcnt lgkmcnt(3)
	v_mfma_f32_32x32x16_bf16 v[50:65], v[198:201], v[130:133], v[50:65]
	ds_read_b128 v[194:197], v228 offset:40448
	v_exp_f32_e32 v224, v104
	v_exp_f32_e32 v225, v105
	v_add_f32_e32 v164, v224, v164
	v_cvt_pk_bf16_f32 v217, v224, v225
	v_add_f32_e32 v164, v225, v164
	s_waitcnt lgkmcnt(3)
	v_mfma_f32_32x32x16_bf16 v[34:49], v[182:185], v[134:137], v[34:49]
	ds_read_b128 v[198:201], v228 offset:35872
	v_exp_f32_e32 v222, v106
	v_exp_f32_e32 v223, v107
	v_add_f32_e32 v164, v222, v164
	v_cvt_pk_bf16_f32 v218, v222, v223
	v_add_f32_e32 v164, v223, v164
	s_waitcnt lgkmcnt(3)
	v_mfma_f32_32x32x16_bf16 v[50:65], v[186:189], v[134:137], v[50:65]
	ds_read_b128 v[182:185], v228 offset:40480
	v_exp_f32_e32 v224, v108
	v_exp_f32_e32 v225, v109
	v_add_f32_e32 v164, v224, v164
	v_cvt_pk_bf16_f32 v219, v224, v225
	v_add_f32_e32 v164, v225, v164
	s_waitcnt lgkmcnt(3)
	v_mfma_f32_32x32x16_bf16 v[2:17], v[190:193], v[206:209], v[2:17]
	ds_read_b128 v[186:189], v228 offset:35904
	v_exp_f32_e32 v222, v110
	v_exp_f32_e32 v223, v111
	v_add_f32_e32 v164, v222, v164
	v_cvt_pk_bf16_f32 v220, v222, v223
	v_add_f32_e32 v164, v223, v164
	s_mov_b32 s13, s20
	s_mov_b32 s20, s19
	s_add_i32 s19, s19, 1
	s_cmp_eq_u32 s19, s9
	s_cselect_b32 s19, 0, s19
	s_waitcnt lgkmcnt(3)
	v_mfma_f32_32x32x16_bf16 v[18:33], v[194:197], v[206:209], v[18:33]
	ds_read_b128 v[190:193], v228 offset:40512
	v_exp_f32_e32 v224, v112
	v_exp_f32_e32 v225, v113
	v_add_f32_e32 v164, v224, v164
	v_cvt_pk_bf16_f32 v221, v224, v225
	v_add_f32_e32 v164, v225, v164
	s_waitcnt vmcnt(2)
	ds_write_b128 v172, v[150:153]
	v_lshl_add_u32 v222, s19, 17, v178
	global_load_dwordx4 v[150:153], v222, s[52:53]
	s_waitcnt lgkmcnt(4)
	v_mfma_f32_32x32x16_bf16 v[2:17], v[198:201], v[210:213], v[2:17]
	ds_read_b128 v[194:197], v228 offset:35936
	v_max3_f32 v224, v34, v35, v36
	v_max3_f32 v225, v50, v51, v52
	v_max3_f32 v224, v224, v37, v38
	v_max3_f32 v225, v225, v53, v54
	s_and_b64 vcc, exec, s[2:3]
	s_cbranch_vccz .Lmla_p1_nope
	ds_write_b128 v176, v[160:163] offset:128
	v_lshl_add_u32 v222, s19, 12, v179
	global_load_dwordx4 v[160:163], v222, s[62:63]
.Lmla_p1_nope:
	s_waitcnt lgkmcnt(4)
	v_mfma_f32_32x32x16_bf16 v[18:33], v[182:185], v[210:213], v[18:33]
	ds_read_b128 v[198:201], v228 offset:40544
	ds_read_b128 v[182:185], v229 offset:13312
	v_max3_f32 v224, v224, v39, v40
	v_max3_f32 v225, v225, v55, v56
	v_max3_f32 v224, v224, v41, v42
	v_max3_f32 v225, v225, v57, v58
	v_add_u32_e32 v222, 0xb000, v173
	ds_write_b128 v222, v[202:205] offset:49152
	v_lshl_add_u32 v222, s13, 7, v168
	global_load_dwordx4 v[202:205], v222, s[56:57]
	s_waitcnt lgkmcnt(6)
	v_mfma_f32_32x32x16_bf16 v[2:17], v[186:189], v[214:217], v[2:17]
	ds_read_b128 v[186:189], v229 offset:19968
	v_max3_f32 v224, v224, v43, v44
	v_max3_f32 v225, v225, v59, v60
	v_max3_f32 v224, v224, v45, v46
	v_max3_f32 v225, v225, v61, v62
	s_waitcnt lgkmcnt(6)
	v_mfma_f32_32x32x16_bf16 v[18:33], v[190:193], v[214:217], v[18:33]
	ds_read_b128 v[190:193], v229 offset:13344
	v_max3_f32 v224, v224, v47, v48
	v_max3_f32 v225, v225, v63, v64
	v_max3_f32 v224, v224, v49, v65
	v_max_f32_e32 v224, v224, v225
	s_waitcnt lgkmcnt(5)
	v_mfma_f32_32x32x16_bf16 v[2:17], v[194:197], v[218:221], v[2:17]
	ds_read_b128 v[194:197], v229 offset:20000
	v_mov_b32_e32 v225, v224
	v_add_f32_e32 v1, v1, v164
	s_add_i32 s11, s11, 1
	v_permlane32_swap_b32_e32 v224, v225
	s_cmp_eq_u32 s9, s11
	v_max_f32_e32 v167, v224, v225
	v_cmp_lt_f32_e32 vcc, s66, v167
	s_waitcnt lgkmcnt(5)
	v_mfma_f32_32x32x16_bf16 v[18:33], v[198:201], v[218:221], v[18:33]
	s_waitcnt lgkmcnt(3)
	s_barrier

; template <int VAR>
; __device__ __forceinline__ void attn_phase(LAS unsigned char* lds, const AttnP P, int vcu, int G, int wave_s) {
;     ...
;                 if (ND0 == 6) {
;                     KR1(0); KR1(1); KR1(2); KR1(3); SB();
;                     QK1(0, negm); EX2(pc0, 0, w0.x); KR1(4); SB();
;                     QK1(1, negm); EX2(pc0, 2, w0.y); KR1(5); SB();
;                     QK1(2, pn0); EX2(pc0, 4, w0.z); KR1(6); SB();
;                     QK1(3, pn1); EX2(pc0, 6, w0.w); KR1(7); SB();
;                     QK1(4, pn0); EX2(pc0, 8, w1.x); KR1(8); SB();
;                     QK1(5, pn1); EX2(pc0, 10, w1.y); KR1(9); SB();
;                     QK1(6, pn0); EX2(pc0, 12, w1.z); KR1(10); SB();
;                     QK1(7, pn1); EX2(pc0, 14, w1.w); KR1(11); SB();
;                     QK1(8, pn0); EX2(pc1, 0, w2.x); VR1(0); SB();
;                     QK1(9, pn1); EX2(pc1, 2, w2.y); VR1(1); SB();
;                     QK1(10, pn0); EX2(pc1, 4, w2.z); VR1(2); SB();
;                     QK1(11, pn1); EX2(pc1, 6, w2.w); VR1(3); SB();
;                 } else {
;                     KR1(0); KR1(1); KR1(2); KR1(3); SB();
;                     QK1(0, negm); EX2(pc0, 0, w0.x); EX2(pc0, 2, w0.y); KR1(4); SB();
;                     QK1(1, negm); EX2(pc0, 4, w0.z); EX2(pc0, 6, w0.w); KR1(5); SB();
;                     QK1(2, pn0); EX2(pc0, 8, w1.x); EX2(pc0, 10, w1.y); KR1(6); SB();
;                     QK1(3, pn1); EX2(pc0, 12, w1.z); EX2(pc0, 14, w1.w); KR1(7); SB();
;                     QK1(4, pn0); EX2(pc1, 0, w2.x); VR1(0); SB();
;                     QK1(5, pn1); EX2(pc1, 2, w2.y); VR1(1); SB();
;                     QK1(6, pn0); EX2(pc1, 4, w2.z); VR1(2); SB();
;                     QK1(7, pn1); EX2(pc1, 6, w2.w); VR1(3); SB();
;                 }
;                 PV1(0, w0); EX2(pc1, 8, w3.x); VR1(4); SB();
;                 PV1(1, w0); EX2(pc1, 10, w3.y); VR1(5); SB();
;                 PV1(2, w1); EX2(pc1, 12, w3.z); VR1(6); SB();
;                 PV1(3, w1); EX2(pc1, 14, w3.w); VR1(7); SB();
;                 lrun += sacc;
;                 PV1(4, w2); MASK_TILE(pn0, pn1, t + 1); SB();
;                 PV1(5, w2); SB();
;                 PV1(6, w3); SB();
;                 PV1(7, w3); rmn = rowmax32(pn0, pn1); if (!USE_NEGM) rmn -= mref; SB();
;     ...
;             if (hn) { STOREK(t & 1); STOREV((t + 1) & 1); }
;             __syncthreads();
.Lmla_p3_go:
	v_exp_f32_e32 v222, v82
	v_exp_f32_e32 v223, v83
	v_add_f32_e32 v164, 0, v222
	v_cvt_pk_bf16_f32 v206, v222, v223
	v_add_f32_e32 v164, v223, v164
	v_exp_f32_e32 v224, v84
	v_exp_f32_e32 v225, v85
	v_add_f32_e32 v164, v224, v164
	v_cvt_pk_bf16_f32 v207, v224, v225
	v_add_f32_e32 v164, v225, v164
	s_waitcnt lgkmcnt(4)
	v_mfma_f32_32x32x16_bf16 v[34:49], v[182:185], v[114:117], v[66:81]
	ds_read_b128 v[198:201], v229 offset:26688
	v_exp_f32_e32 v222, v86
	v_exp_f32_e32 v223, v87
	v_add_f32_e32 v164, v222, v164
	v_cvt_pk_bf16_f32 v208, v222, v223
	v_add_f32_e32 v164, v223, v164
	s_waitcnt lgkmcnt(4)
	v_mfma_f32_32x32x16_bf16 v[50:65], v[186:189], v[114:117], v[66:81]
	ds_read_b128 v[182:185], v229 offset:33344
	v_exp_f32_e32 v224, v88
	v_exp_f32_e32 v225, v89
	v_add_f32_e32 v164, v224, v164
	v_cvt_pk_bf16_f32 v209, v224, v225
	v_add_f32_e32 v164, v225, v164
	s_waitcnt lgkmcnt(3)
	v_mfma_f32_32x32x16_bf16 v[34:49], v[190:193], v[118:121], v[34:49]
	ds_read_b128 v[186:189], v229 offset:26720
	v_exp_f32_e32 v222, v90
	v_exp_f32_e32 v223, v91
	v_add_f32_e32 v164, v222, v164
	v_cvt_pk_bf16_f32 v210, v222, v223
	v_add_f32_e32 v164, v223, v164
	s_waitcnt lgkmcnt(3)
	v_mfma_f32_32x32x16_bf16 v[50:65], v[194:197], v[118:121], v[50:65]
	ds_read_b128 v[190:193], v229 offset:33376
	v_exp_f32_e32 v224, v92
	v_exp_f32_e32 v225, v93
	v_add_f32_e32 v164, v224, v164
	v_cvt_pk_bf16_f32 v211, v224, v225
	v_add_f32_e32 v164, v225, v164
	s_waitcnt lgkmcnt(3)
	v_mfma_f32_32x32x16_bf16 v[34:49], v[198:201], v[122:125], v[34:49]
	ds_read_b128 v[194:197], v229 offset:26752
	v_exp_f32_e32 v222, v94
	v_exp_f32_e32 v223, v95
	v_add_f32_e32 v164, v222, v164
	v_cvt_pk_bf16_f32 v212, v222, v223
	v_add_f32_e32 v164, v223, v164
	s_waitcnt lgkmcnt(3)
	v_mfma_f32_32x32x16_bf16 v[50:65], v[182:185], v[122:125], v[50:65]
	ds_read_b128 v[198:201], v229 offset:33408
	v_exp_f32_e32 v224, v96
	v_exp_f32_e32 v225, v97
	v_add_f32_e32 v164, v224, v164
	v_cvt_pk_bf16_f32 v213, v224, v225
	v_add_f32_e32 v164, v225, v164
	s_waitcnt lgkmcnt(3)
	v_mfma_f32_32x32x16_bf16 v[34:49], v[186:189], v[126:129], v[34:49]
	ds_read_b128 v[182:185], v229 offset:26784
	v_exp_f32_e32 v222, v98
	v_exp_f32_e32 v223, v99
	v_add_f32_e32 v164, v222, v164
	v_cvt_pk_bf16_f32 v214, v222, v223
	v_add_f32_e32 v164, v223, v164
	s_waitcnt lgkmcnt(3)
	v_mfma_f32_32x32x16_bf16 v[50:65], v[190:193], v[126:129], v[50:65]
	ds_read_b128 v[186:189], v229 offset:33440
	v_exp_f32_e32 v224, v100
	v_exp_f32_e32 v225, v101
	v_add_f32_e32 v164, v224, v164
	v_cvt_pk_bf16_f32 v215, v224, v225
	v_add_f32_e32 v164, v225, v164
	s_waitcnt lgkmcnt(3)
	v_mfma_f32_32x32x16_bf16 v[34:49], v[194:197], v[130:133], v[34:49]
	ds_read_b128 v[190:193], v181 offset:49152
	v_exp_f32_e32 v222, v102
	v_exp_f32_e32 v223, v103
	v_add_f32_e32 v164, v222, v164
	v_cvt_pk_bf16_f32 v216, v222, v223
	v_add_f32_e32 v164, v223, v164
	s_waitcnt lgkmcnt(3)
	v_mfma_f32_32x32x16_bf16 v[50:65], v[198:201], v[130:133], v[50:65]
	ds_read_b128 v[194:197], v181 offset:53760
	v_exp_f32_e32 v224, v104
	v_exp_f32_e32 v225, v105
	v_add_f32_e32 v164, v224, v164
	v_cvt_pk_bf16_f32 v217, v224, v225
	v_add_f32_e32 v164, v225, v164
	s_waitcnt lgkmcnt(3)
	v_mfma_f32_32x32x16_bf16 v[34:49], v[182:185], v[134:137], v[34:49]
	ds_read_b128 v[198:201], v181 offset:49184
	v_exp_f32_e32 v222, v106
	v_exp_f32_e32 v223, v107
	v_add_f32_e32 v164, v222, v164
	v_cvt_pk_bf16_f32 v218, v222, v223
	v_add_f32_e32 v164, v223, v164
	s_waitcnt lgkmcnt(3)
	v_mfma_f32_32x32x16_bf16 v[50:65], v[186:189], v[134:137], v[50:65]
	ds_read_b128 v[182:185], v181 offset:53792
	v_exp_f32_e32 v224, v108
	v_exp_f32_e32 v225, v109
	v_add_f32_e32 v164, v224, v164
	v_cvt_pk_bf16_f32 v219, v224, v225
	v_add_f32_e32 v164, v225, v164
	s_waitcnt lgkmcnt(3)
	v_mfma_f32_32x32x16_bf16 v[2:17], v[190:193], v[206:209], v[2:17]
	ds_read_b128 v[186:189], v181 offset:49216
	v_exp_f32_e32 v222, v110
	v_exp_f32_e32 v223, v111
	v_add_f32_e32 v164, v222, v164
	v_cvt_pk_bf16_f32 v220, v222, v223
	v_add_f32_e32 v164, v223, v164
	s_mov_b32 s13, s20
	s_mov_b32 s20, s19
	s_add_i32 s19, s19, 1
	s_cmp_eq_u32 s19, s9
	s_cselect_b32 s19, 0, s19
	s_waitcnt lgkmcnt(3)
	v_mfma_f32_32x32x16_bf16 v[18:33], v[194:197], v[206:209], v[18:33]
	ds_read_b128 v[190:193], v181 offset:53824
	v_exp_f32_e32 v224, v112
	v_exp_f32_e32 v225, v113
	v_add_f32_e32 v164, v224, v164
	v_cvt_pk_bf16_f32 v221, v224, v225
	v_add_f32_e32 v164, v225, v164
	s_waitcnt vmcnt(2)
	ds_write_b128 v172, v[150:153] offset:45056
	v_lshl_add_u32 v222, s19, 17, v178
	global_load_dwordx4 v[150:153], v222, s[52:53]
	s_waitcnt lgkmcnt(4)
	v_mfma_f32_32x32x16_bf16 v[2:17], v[198:201], v[210:213], v[2:17]
	ds_read_b128 v[194:197], v181 offset:49248
	v_max3_f32 v224, v34, v35, v36
	v_max3_f32 v225, v50, v51, v52
	v_max3_f32 v224, v224, v37, v38
	v_max3_f32 v225, v225, v53, v54
	s_and_b64 vcc, exec, s[2:3]
	s_cbranch_vccz .Lmla_p3_nope
	ds_write_b128 v176, v[160:163] offset:45184
	v_lshl_add_u32 v222, s19, 12, v179
	global_load_dwordx4 v[160:163], v222, s[62:63]
.Lmla_p3_nope:
	s_waitcnt lgkmcnt(4)
	v_mfma_f32_32x32x16_bf16 v[18:33], v[182:185], v[210:213], v[18:33]
	ds_read_b128 v[198:201], v181 offset:53856
	ds_read_b128 v[182:185], v174
	v_max3_f32 v224, v224, v39, v40
	v_max3_f32 v225, v225, v55, v56
	v_max3_f32 v224, v224, v41, v42
	v_max3_f32 v225, v225, v57, v58
	ds_write_b128 v173, v[202:205] offset:35840
	v_lshl_add_u32 v222, s13, 7, v168
	global_load_dwordx4 v[202:205], v222, s[56:57]
	s_waitcnt lgkmcnt(6)
	v_mfma_f32_32x32x16_bf16 v[2:17], v[186:189], v[214:217], v[2:17]
	ds_read_b128 v[186:189], v174 offset:6656
	v_max3_f32 v224, v224, v43, v44
	v_max3_f32 v225, v225, v59, v60
	v_max3_f32 v224, v224, v45, v46
	v_max3_f32 v225, v225, v61, v62
	s_waitcnt lgkmcnt(6)
	v_mfma_f32_32x32x16_bf16 v[18:33], v[190:193], v[214:217], v[18:33]
	ds_read_b128 v[190:193], v174 offset:32
	v_max3_f32 v224, v224, v47, v48
	v_max3_f32 v225, v225, v63, v64
	v_max3_f32 v224, v224, v49, v65
	v_max_f32_e32 v224, v224, v225
	s_waitcnt lgkmcnt(5)
	v_mfma_f32_32x32x16_bf16 v[2:17], v[194:197], v[218:221], v[2:17]
	ds_read_b128 v[194:197], v174 offset:6688
	v_mov_b32_e32 v225, v224
	v_add_f32_e32 v1, v1, v164
	s_add_i32 s11, s11, 1
	v_permlane32_swap_b32_e32 v224, v225
	s_cmp_eq_u32 s9, s11
	v_max_f32_e32 v167, v224, v225
	v_cmp_lt_f32_e32 vcc, s66, v167
	s_waitcnt lgkmcnt(5)
	v_mfma_f32_32x32x16_bf16 v[18:33], v[198:201], v[218:221], v[18:33]
	s_waitcnt lgkmcnt(3)
	s_barrier

; template <int VAR>
; __device__ __forceinline__ void attn_phase(LAS unsigned char* lds, const AttnP P, int vcu, int G, int wave_s) {
;     ...
;                 if (ND0 == 6) {
;                     KR1(0); KR1(1); KR1(2); KR1(3); SB();
;                     QK1(0, negm); EX2(pc0, 0, w0.x); KR1(4); SB();
;                     QK1(1, negm); EX2(pc0, 2, w0.y); KR1(5); SB();
;                     QK1(2, pn0); EX2(pc0, 4, w0.z); KR1(6); SB();
;                     QK1(3, pn1); EX2(pc0, 6, w0.w); KR1(7); SB();
;                     QK1(4, pn0); EX2(pc0, 8, w1.x); KR1(8); SB();
;                     QK1(5, pn1); EX2(pc0, 10, w1.y); KR1(9); SB();
;                     QK1(6, pn0); EX2(pc0, 12, w1.z); KR1(10); SB();
;                     QK1(7, pn1); EX2(pc0, 14, w1.w); KR1(11); SB();
;                     QK1(8, pn0); EX2(pc1, 0, w2.x); VR1(0); SB();
;                     QK1(9, pn1); EX2(pc1, 2, w2.y); VR1(1); SB();
;                     QK1(10, pn0); EX2(pc1, 4, w2.z); VR1(2); SB();
;                     QK1(11, pn1); EX2(pc1, 6, w2.w); VR1(3); SB();
;                 } else {
;                     KR1(0); KR1(1); KR1(2); KR1(3); SB();
;                     QK1(0, negm); EX2(pc0, 0, w0.x); EX2(pc0, 2, w0.y); KR1(4); SB();
;                     QK1(1, negm); EX2(pc0, 4, w0.z); EX2(pc0, 6, w0.w); KR1(5); SB();
;                     QK1(2, pn0); EX2(pc0, 8, w1.x); EX2(pc0, 10, w1.y); KR1(6); SB();
;                     QK1(3, pn1); EX2(pc0, 12, w1.z); EX2(pc0, 14, w1.w); KR1(7); SB();
;                     QK1(4, pn0); EX2(pc1, 0, w2.x); VR1(0); SB();
;                     QK1(5, pn1); EX2(pc1, 2, w2.y); VR1(1); SB();
;                     QK1(6, pn0); EX2(pc1, 4, w2.z); VR1(2); SB();
;                     QK1(7, pn1); EX2(pc1, 6, w2.w); VR1(3); SB();
;                 }
;                 PV1(0, w0); EX2(pc1, 8, w3.x); VR1(4); SB();
;                 PV1(1, w0); EX2(pc1, 10, w3.y); VR1(5); SB();
;                 PV1(2, w1); EX2(pc1, 12, w3.z); VR1(6); SB();
;                 PV1(3, w1); EX2(pc1, 14, w3.w); VR1(7); SB();
;                 lrun += sacc;
;                 PV1(4, w2); MASK_TILE(pn0, pn1, t + 1); SB();
;                 PV1(5, w2); SB();
;                 PV1(6, w3); SB();
;                 PV1(7, w3); rmn = rowmax32(pn0, pn1); if (!USE_NEGM) rmn -= mref; SB();
;     ...
;             if (hn) { STOREK(t & 1); STOREV((t + 1) & 1); }
;             __syncthreads();
.Lmla_p5_go:
	v_exp_f32_e32 v222, v82
	v_exp_f32_e32 v223, v83
	v_add_f32_e32 v164, 0, v222
	v_cvt_pk_bf16_f32 v206, v222, v223
	v_add_f32_e32 v164, v223, v164
	v_exp_f32_e32 v224, v84
	v_exp_f32_e32 v225, v85
	v_add_f32_e32 v164, v224, v164
	v_cvt_pk_bf16_f32 v207, v224, v225
	v_add_f32_e32 v164, v225, v164
	s_waitcnt lgkmcnt(4)
	v_mfma_f32_32x32x16_bf16 v[34:49], v[182:185], v[114:117], v[66:81]
	ds_read_b128 v[198:201], v174 offset:22592
	v_exp_f32_e32 v222, v86
	v_exp_f32_e32 v223, v87
	v_add_f32_e32 v164, v222, v164
	v_cvt_pk_bf16_f32 v208, v222, v223
	v_add_f32_e32 v164, v223, v164
	s_waitcnt lgkmcnt(4)
	v_mfma_f32_32x32x16_bf16 v[50:65], v[186:189], v[114:117], v[66:81]
	ds_read_b128 v[182:185], v174 offset:29248
	v_exp_f32_e32 v224, v88
	v_exp_f32_e32 v225, v89
	v_add_f32_e32 v164, v224, v164
	v_cvt_pk_bf16_f32 v209, v224, v225
	v_add_f32_e32 v164, v225, v164
	s_waitcnt lgkmcnt(3)
	v_mfma_f32_32x32x16_bf16 v[34:49], v[190:193], v[118:121], v[34:49]
	ds_read_b128 v[186:189], v174 offset:22624
	v_exp_f32_e32 v222, v90
	v_exp_f32_e32 v223, v91
	v_add_f32_e32 v164, v222, v164
	v_cvt_pk_bf16_f32 v210, v222, v223
	v_add_f32_e32 v164, v223, v164
	s_waitcnt lgkmcnt(3)
	v_mfma_f32_32x32x16_bf16 v[50:65], v[194:197], v[118:121], v[50:65]
	ds_read_b128 v[190:193], v174 offset:29280
	v_exp_f32_e32 v224, v92
	v_exp_f32_e32 v225, v93
	v_add_f32_e32 v164, v224, v164
	v_cvt_pk_bf16_f32 v211, v224, v225
	v_add_f32_e32 v164, v225, v164
	s_waitcnt lgkmcnt(3)
	v_mfma_f32_32x32x16_bf16 v[34:49], v[198:201], v[122:125], v[34:49]
	ds_read_b128 v[194:197], v174 offset:22656
	v_exp_f32_e32 v222, v94
	v_exp_f32_e32 v223, v95
	v_add_f32_e32 v164, v222, v164
	v_cvt_pk_bf16_f32 v212, v222, v223
	v_add_f32_e32 v164, v223, v164
	s_waitcnt lgkmcnt(3)
	v_mfma_f32_32x32x16_bf16 v[50:65], v[182:185], v[122:125], v[50:65]
	ds_read_b128 v[198:201], v174 offset:29312
	v_exp_f32_e32 v224, v96
	v_exp_f32_e32 v225, v97
	v_add_f32_e32 v164, v224, v164
	v_cvt_pk_bf16_f32 v213, v224, v225
	v_add_f32_e32 v164, v225, v164
	s_waitcnt lgkmcnt(3)
	v_mfma_f32_32x32x16_bf16 v[34:49], v[186:189], v[126:129], v[34:49]
	ds_read_b128 v[182:185], v174 offset:22688
	v_exp_f32_e32 v222, v98
	v_exp_f32_e32 v223, v99
	v_add_f32_e32 v164, v222, v164
	v_cvt_pk_bf16_f32 v214, v222, v223
	v_add_f32_e32 v164, v223, v164
	s_waitcnt lgkmcnt(3)
	v_mfma_f32_32x32x16_bf16 v[50:65], v[190:193], v[126:129], v[50:65]
	ds_read_b128 v[186:189], v174 offset:29344
	v_exp_f32_e32 v224, v100
	v_exp_f32_e32 v225, v101
	v_add_f32_e32 v164, v224, v164
	v_cvt_pk_bf16_f32 v215, v224, v225
	v_add_f32_e32 v164, v225, v164
	s_waitcnt lgkmcnt(3)
	v_mfma_f32_32x32x16_bf16 v[34:49], v[194:197], v[130:133], v[34:49]
	ds_read_b128 v[190:193], v228 offset:35840
	v_exp_f32_e32 v222, v102
	v_exp_f32_e32 v223, v103
	v_add_f32_e32 v164, v222, v164
	v_cvt_pk_bf16_f32 v216, v222, v223
	v_add_f32_e32 v164, v223, v164
	s_waitcnt lgkmcnt(3)
	v_mfma_f32_32x32x16_bf16 v[50:65], v[198:201], v[130:133], v[50:65]
	ds_read_b128 v[194:197], v228 offset:40448
	v_exp_f32_e32 v224, v104
	v_exp_f32_e32 v225, v105
	v_add_f32_e32 v164, v224, v164
	v_cvt_pk_bf16_f32 v217, v224, v225
	v_add_f32_e32 v164, v225, v164
	s_waitcnt lgkmcnt(3)
	v_mfma_f32_32x32x16_bf16 v[34:49], v[182:185], v[134:137], v[34:49]
	ds_read_b128 v[198:201], v228 offset:35872
	v_exp_f32_e32 v222, v106
	v_exp_f32_e32 v223, v107
	v_add_f32_e32 v164, v222, v164
	v_cvt_pk_bf16_f32 v218, v222, v223
	v_add_f32_e32 v164, v223, v164
	s_waitcnt lgkmcnt(3)
	v_mfma_f32_32x32x16_bf16 v[50:65], v[186:189], v[134:137], v[50:65]
	ds_read_b128 v[182:185], v228 offset:40480
	v_exp_f32_e32 v224, v108
	v_exp_f32_e32 v225, v109
	v_add_f32_e32 v164, v224, v164
	v_cvt_pk_bf16_f32 v219, v224, v225
	v_add_f32_e32 v164, v225, v164
	s_waitcnt lgkmcnt(3)
	v_mfma_f32_32x32x16_bf16 v[2:17], v[190:193], v[206:209], v[2:17]
	ds_read_b128 v[186:189], v228 offset:35904
	v_exp_f32_e32 v222, v110
	v_exp_f32_e32 v223, v111
	v_add_f32_e32 v164, v222, v164
	v_cvt_pk_bf16_f32 v220, v222, v223
	v_add_f32_e32 v164, v223, v164
	s_mov_b32 s13, s20
	s_mov_b32 s20, s19
	s_add_i32 s19, s19, 1
	s_cmp_eq_u32 s19, s9
	s_cselect_b32 s19, 0, s19
	s_waitcnt lgkmcnt(3)
	v_mfma_f32_32x32x16_bf16 v[18:33], v[194:197], v[206:209], v[18:33]
	ds_read_b128 v[190:193], v228 offset:40512
	v_exp_f32_e32 v224, v112
	v_exp_f32_e32 v225, v113
	v_add_f32_e32 v164, v224, v164
	v_cvt_pk_bf16_f32 v221, v224, v225
	v_add_f32_e32 v164, v225, v164
	s_waitcnt vmcnt(2)
	v_add_u32_e32 v222, 0xb000, v172
	ds_write_b128 v222, v[150:153] offset:26624
	v_lshl_add_u32 v222, s19, 17, v178
	global_load_dwordx4 v[150:153], v222, s[52:53]
	s_waitcnt lgkmcnt(4)
	v_mfma_f32_32x32x16_bf16 v[2:17], v[198:201], v[210:213], v[2:17]
	ds_read_b128 v[194:197], v228 offset:35936
	v_max3_f32 v224, v34, v35, v36
	v_max3_f32 v225, v50, v51, v52
	v_max3_f32 v224, v224, v37, v38
	v_max3_f32 v225, v225, v53, v54
	s_and_b64 vcc, exec, s[2:3]
	s_cbranch_vccz .Lmla_p5_nope
	v_add_u32_e32 v222, 0xb000, v176
	ds_write_b128 v222, v[160:163] offset:26752
	v_lshl_add_u32 v222, s19, 12, v179
	global_load_dwordx4 v[160:163], v222, s[62:63]
.Lmla_p5_nope:
	s_waitcnt lgkmcnt(4)
	v_mfma_f32_32x32x16_bf16 v[18:33], v[182:185], v[210:213], v[18:33]
	ds_read_b128 v[198:201], v228 offset:40544
	ds_read_b128 v[182:185], v174 offset:45056
	v_max3_f32 v224, v224, v39, v40
	v_max3_f32 v225, v225, v55, v56
	v_max3_f32 v224, v224, v41, v42
	v_max3_f32 v225, v225, v57, v58
	v_add_u32_e32 v222, 0xb000, v173
	ds_write_b128 v222, v[202:205] offset:49152
	v_lshl_add_u32 v222, s13, 7, v168
	global_load_dwordx4 v[202:205], v222, s[56:57]
	s_waitcnt lgkmcnt(6)
	v_mfma_f32_32x32x16_bf16 v[2:17], v[186:189], v[214:217], v[2:17]
	ds_read_b128 v[186:189], v174 offset:51712
	v_max3_f32 v224, v224, v43, v44
	v_max3_f32 v225, v225, v59, v60
	v_max3_f32 v224, v224, v45, v46
	v_max3_f32 v225, v225, v61, v62
	s_waitcnt lgkmcnt(6)
	v_mfma_f32_32x32x16_bf16 v[18:33], v[190:193], v[214:217], v[18:33]
	ds_read_b128 v[190:193], v174 offset:45088
	v_max3_f32 v224, v224, v47, v48
	v_max3_f32 v225, v225, v63, v64
	v_max3_f32 v224, v224, v49, v65
	v_max_f32_e32 v224, v224, v225
	s_waitcnt lgkmcnt(5)
	v_mfma_f32_32x32x16_bf16 v[2:17], v[194:197], v[218:221], v[2:17]
	ds_read_b128 v[194:197], v174 offset:51744
	v_mov_b32_e32 v225, v224
	v_add_f32_e32 v1, v1, v164
	s_add_i32 s11, s11, 1
	v_permlane32_swap_b32_e32 v224, v225
	s_cmp_eq_u32 s9, s11
	v_max_f32_e32 v167, v224, v225
	v_cmp_lt_f32_e32 vcc, s66, v167
	s_waitcnt lgkmcnt(5)
	v_mfma_f32_32x32x16_bf16 v[18:33], v[198:201], v[218:221], v[18:33]
	s_waitcnt lgkmcnt(3)
	s_barrier

; template <int VAR>
; __device__ __forceinline__ void attn_phase(LAS unsigned char* lds, const AttnP P, int vcu, int G, int wave_s) {
;     ...
;                 if (ND0 == 6) {
;                     KR1(0); KR1(1); KR1(2); KR1(3); SB();
;                     QK1(0, negm); EX2(pc0, 0, w0.x); KR1(4); SB();
;                     QK1(1, negm); EX2(pc0, 2, w0.y); KR1(5); SB();
;                     QK1(2, pn0); EX2(pc0, 4, w0.z); KR1(6); SB();
;                     QK1(3, pn1); EX2(pc0, 6, w0.w); KR1(7); SB();
;                     QK1(4, pn0); EX2(pc0, 8, w1.x); KR1(8); SB();
;                     QK1(5, pn1); EX2(pc0, 10, w1.y); KR1(9); SB();
;                     QK1(6, pn0); EX2(pc0, 12, w1.z); KR1(10); SB();
;                     QK1(7, pn1); EX2(pc0, 14, w1.w); KR1(11); SB();
;                     QK1(8, pn0); EX2(pc1, 0, w2.x); VR1(0); SB();
;                     QK1(9, pn1); EX2(pc1, 2, w2.y); VR1(1); SB();
;                     QK1(10, pn0); EX2(pc1, 4, w2.z); VR1(2); SB();
;                     QK1(11, pn1); EX2(pc1, 6, w2.w); VR1(3); SB();
;                 } else {
;                     KR1(0); KR1(1); KR1(2); KR1(3); SB();
;                     QK1(0, negm); EX2(pc0, 0, w0.x); EX2(pc0, 2, w0.y); KR1(4); SB();
;                     QK1(1, negm); EX2(pc0, 4, w0.z); EX2(pc0, 6, w0.w); KR1(5); SB();
;                     QK1(2, pn0); EX2(pc0, 8, w1.x); EX2(pc0, 10, w1.y); KR1(6); SB();
;                     QK1(3, pn1); EX2(pc0, 12, w1.z); EX2(pc0, 14, w1.w); KR1(7); SB();
;                     QK1(4, pn0); EX2(pc1, 0, w2.x); VR1(0); SB();
;                     QK1(5, pn1); EX2(pc1, 2, w2.y); VR1(1); SB();
;                     QK1(6, pn0); EX2(pc1, 4, w2.z); VR1(2); SB();
;                     QK1(7, pn1); EX2(pc1, 6, w2.w); VR1(3); SB();
;                 }
;                 PV1(0, w0); EX2(pc1, 8, w3.x); VR1(4); SB();
;                 PV1(1, w0); EX2(pc1, 10, w3.y); VR1(5); SB();
;                 PV1(2, w1); EX2(pc1, 12, w3.z); VR1(6); SB();
;                 PV1(3, w1); EX2(pc1, 14, w3.w); VR1(7); SB();
;                 lrun += sacc;
;                 PV1(4, w2); MASK_TILE(pn0, pn1, t + 1); SB();
;                 PV1(5, w2); SB();
;                 PV1(6, w3); SB();
;                 PV1(7, w3); rmn = rowmax32(pn0, pn1); if (!USE_NEGM) rmn -= mref; SB();
;     ...
;             if (hn) { STOREK(t & 1); STOREV((t + 1) & 1); }
;             __syncthreads();
.Lmla_p7_go:
	v_exp_f32_e32 v222, v82
	v_exp_f32_e32 v223, v83
	v_add_f32_e32 v164, 0, v222
	v_cvt_pk_bf16_f32 v206, v222, v223
	v_add_f32_e32 v164, v223, v164
	v_exp_f32_e32 v224, v84
	v_exp_f32_e32 v225, v85
	v_add_f32_e32 v164, v224, v164
	v_cvt_pk_bf16_f32 v207, v224, v225
	v_add_f32_e32 v164, v225, v164
	s_waitcnt lgkmcnt(4)
	v_mfma_f32_32x32x16_bf16 v[34:49], v[182:185], v[114:117], v[66:81]
	ds_read_b128 v[198:201], v229 offset:13376
	v_exp_f32_e32 v222, v86
	v_exp_f32_e32 v223, v87
	v_add_f32_e32 v164, v222, v164
	v_cvt_pk_bf16_f32 v208, v222, v223
	v_add_f32_e32 v164, v223, v164
	s_waitcnt lgkmcnt(4)
	v_mfma_f32_32x32x16_bf16 v[50:65], v[186:189], v[114:117], v[66:81]
	ds_read_b128 v[182:185], v229 offset:20032
	v_exp_f32_e32 v224, v88
	v_exp_f32_e32 v225, v89
	v_add_f32_e32 v164, v224, v164
	v_cvt_pk_bf16_f32 v209, v224, v225
	v_add_f32_e32 v164, v225, v164
	s_waitcnt lgkmcnt(3)
	v_mfma_f32_32x32x16_bf16 v[34:49], v[190:193], v[118:121], v[34:49]
	ds_read_b128 v[186:189], v229 offset:13408
	v_exp_f32_e32 v222, v90
	v_exp_f32_e32 v223, v91
	v_add_f32_e32 v164, v222, v164
	v_cvt_pk_bf16_f32 v210, v222, v223
	v_add_f32_e32 v164, v223, v164
	s_waitcnt lgkmcnt(3)
	v_mfma_f32_32x32x16_bf16 v[50:65], v[194:197], v[118:121], v[50:65]
	ds_read_b128 v[190:193], v229 offset:20064
	v_exp_f32_e32 v224, v92
	v_exp_f32_e32 v225, v93
	v_add_f32_e32 v164, v224, v164
	v_cvt_pk_bf16_f32 v211, v224, v225
	v_add_f32_e32 v164, v225, v164
	s_waitcnt lgkmcnt(3)
	v_mfma_f32_32x32x16_bf16 v[34:49], v[198:201], v[122:125], v[34:49]
	ds_read_b128 v[194:197], v229 offset:13440
	v_exp_f32_e32 v222, v94
	v_exp_f32_e32 v223, v95
	v_add_f32_e32 v164, v222, v164
	v_cvt_pk_bf16_f32 v212, v222, v223
	v_add_f32_e32 v164, v223, v164
	s_waitcnt lgkmcnt(3)
	v_mfma_f32_32x32x16_bf16 v[50:65], v[182:185], v[122:125], v[50:65]
	ds_read_b128 v[198:201], v229 offset:20096
	v_exp_f32_e32 v224, v96
	v_exp_f32_e32 v225, v97
	v_add_f32_e32 v164, v224, v164
	v_cvt_pk_bf16_f32 v213, v224, v225
	v_add_f32_e32 v164, v225, v164
	s_waitcnt lgkmcnt(3)
	v_mfma_f32_32x32x16_bf16 v[34:49], v[186:189], v[126:129], v[34:49]
	ds_read_b128 v[182:185], v229 offset:13472
	v_exp_f32_e32 v222, v98
	v_exp_f32_e32 v223, v99
	v_add_f32_e32 v164, v222, v164
	v_cvt_pk_bf16_f32 v214, v222, v223
	v_add_f32_e32 v164, v223, v164
	s_waitcnt lgkmcnt(3)
	v_mfma_f32_32x32x16_bf16 v[50:65], v[190:193], v[126:129], v[50:65]
	ds_read_b128 v[186:189], v229 offset:20128
	v_exp_f32_e32 v224, v100
	v_exp_f32_e32 v225, v101
	v_add_f32_e32 v164, v224, v164
	v_cvt_pk_bf16_f32 v215, v224, v225
	v_add_f32_e32 v164, v225, v164
	s_waitcnt lgkmcnt(3)
	v_mfma_f32_32x32x16_bf16 v[34:49], v[194:197], v[130:133], v[34:49]
	ds_read_b128 v[190:193], v181 offset:49152
	v_exp_f32_e32 v222, v102
	v_exp_f32_e32 v223, v103
	v_add_f32_e32 v164, v222, v164
	v_cvt_pk_bf16_f32 v216, v222, v223
	v_add_f32_e32 v164, v223, v164
	s_waitcnt lgkmcnt(3)
	v_mfma_f32_32x32x16_bf16 v[50:65], v[198:201], v[130:133], v[50:65]
	ds_read_b128 v[194:197], v181 offset:53760
	v_exp_f32_e32 v224, v104
	v_exp_f32_e32 v225, v105
	v_add_f32_e32 v164, v224, v164
	v_cvt_pk_bf16_f32 v217, v224, v225
	v_add_f32_e32 v164, v225, v164
	s_waitcnt lgkmcnt(3)
	v_mfma_f32_32x32x16_bf16 v[34:49], v[182:185], v[134:137], v[34:49]
	ds_read_b128 v[198:201], v181 offset:49184
	v_exp_f32_e32 v222, v106
	v_exp_f32_e32 v223, v107
	v_add_f32_e32 v164, v222, v164
	v_cvt_pk_bf16_f32 v218, v222, v223
	v_add_f32_e32 v164, v223, v164
	s_waitcnt lgkmcnt(3)
	v_mfma_f32_32x32x16_bf16 v[50:65], v[186:189], v[134:137], v[50:65]
	ds_read_b128 v[182:185], v181 offset:53792
	v_exp_f32_e32 v224, v108
	v_exp_f32_e32 v225, v109
	v_add_f32_e32 v164, v224, v164
	v_cvt_pk_bf16_f32 v219, v224, v225
	v_add_f32_e32 v164, v225, v164
	s_waitcnt lgkmcnt(3)
	v_mfma_f32_32x32x16_bf16 v[2:17], v[190:193], v[206:209], v[2:17]
	ds_read_b128 v[186:189], v181 offset:49216
	v_exp_f32_e32 v222, v110
	v_exp_f32_e32 v223, v111
	v_add_f32_e32 v164, v222, v164
	v_cvt_pk_bf16_f32 v220, v222, v223
	v_add_f32_e32 v164, v223, v164
	s_mov_b32 s13, s20
	s_mov_b32 s20, s19
	s_add_i32 s19, s19, 1
	s_cmp_eq_u32 s19, s9
	s_cselect_b32 s19, 0, s19
	s_waitcnt lgkmcnt(3)
	v_mfma_f32_32x32x16_bf16 v[18:33], v[194:197], v[206:209], v[18:33]
	ds_read_b128 v[190:193], v181 offset:53824
	v_exp_f32_e32 v224, v112
	v_exp_f32_e32 v225, v113
	v_add_f32_e32 v164, v224, v164
	v_cvt_pk_bf16_f32 v221, v224, v225
	v_add_f32_e32 v164, v225, v164
	s_waitcnt vmcnt(2)
	ds_write_b128 v172, v[150:153] offset:22528
	v_lshl_add_u32 v222, s19, 17, v178
	global_load_dwordx4 v[150:153], v222, s[52:53]
	s_waitcnt lgkmcnt(4)
	v_mfma_f32_32x32x16_bf16 v[2:17], v[198:201], v[210:213], v[2:17]
	ds_read_b128 v[194:197], v181 offset:49248
	v_max3_f32 v224, v34, v35, v36
	v_max3_f32 v225, v50, v51, v52
	v_max3_f32 v224, v224, v37, v38
	v_max3_f32 v225, v225, v53, v54
	s_and_b64 vcc, exec, s[2:3]
	s_cbranch_vccz .Lmla_p7_nope
	ds_write_b128 v176, v[160:163] offset:22656
	v_lshl_add_u32 v222, s19, 12, v179
	global_load_dwordx4 v[160:163], v222, s[62:63]
.Lmla_p7_nope:
	s_waitcnt lgkmcnt(4)
	v_mfma_f32_32x32x16_bf16 v[18:33], v[182:185], v[210:213], v[18:33]
	ds_read_b128 v[198:201], v181 offset:53856
	ds_read_b128 v[182:185], v229 offset:26624
	v_max3_f32 v224, v224, v39, v40
	v_max3_f32 v225, v225, v55, v56
	v_max3_f32 v224, v224, v41, v42
	v_max3_f32 v225, v225, v57, v58
	ds_write_b128 v173, v[202:205] offset:35840
	v_lshl_add_u32 v222, s13, 7, v168
	global_load_dwordx4 v[202:205], v222, s[56:57]
	s_waitcnt lgkmcnt(6)
	v_mfma_f32_32x32x16_bf16 v[2:17], v[186:189], v[214:217], v[2:17]
	ds_read_b128 v[186:189], v229 offset:33280
	v_max3_f32 v224, v224, v43, v44
	v_max3_f32 v225, v225, v59, v60
	v_max3_f32 v224, v224, v45, v46
	v_max3_f32 v225, v225, v61, v62
	s_waitcnt lgkmcnt(6)
	v_mfma_f32_32x32x16_bf16 v[18:33], v[190:193], v[214:217], v[18:33]
	ds_read_b128 v[190:193], v229 offset:26656
	v_max3_f32 v224, v224, v47, v48
	v_max3_f32 v225, v225, v63, v64
	v_max3_f32 v224, v224, v49, v65
	v_max_f32_e32 v224, v224, v225
	s_waitcnt lgkmcnt(5)
	v_mfma_f32_32x32x16_bf16 v[2:17], v[194:197], v[218:221], v[2:17]
	ds_read_b128 v[194:197], v229 offset:33312
	v_mov_b32_e32 v225, v224
	v_add_f32_e32 v1, v1, v164
	s_add_i32 s11, s11, 1
	v_permlane32_swap_b32_e32 v224, v225
	s_cmp_eq_u32 s9, s11
	v_max_f32_e32 v167, v224, v225
	v_cmp_lt_f32_e32 vcc, s66, v167
	s_waitcnt lgkmcnt(5)
	v_mfma_f32_32x32x16_bf16 v[18:33], v[198:201], v[218:221], v[18:33]
	s_waitcnt lgkmcnt(3)
	s_barrier

; template <int VAR>
; __device__ __forceinline__ void attn_phase(LAS unsigned char* lds, const AttnP P, int vcu, int G, int wave_s) {
;     ...
;                 if (ND0 == 6) {
;                     KR1(0); KR1(1); KR1(2); KR1(3); SB();
;                     QK1(0, negm); EX2(pc0, 0, w0.x); KR1(4); SB();
;                     QK1(1, negm); EX2(pc0, 2, w0.y); KR1(5); SB();
;                     QK1(2, pn0); EX2(pc0, 4, w0.z); KR1(6); SB();
;                     QK1(3, pn1); EX2(pc0, 6, w0.w); KR1(7); SB();
;                     QK1(4, pn0); EX2(pc0, 8, w1.x); KR1(8); SB();
;                     QK1(5, pn1); EX2(pc0, 10, w1.y); KR1(9); SB();
;                     QK1(6, pn0); EX2(pc0, 12, w1.z); KR1(10); SB();
;                     QK1(7, pn1); EX2(pc0, 14, w1.w); KR1(11); SB();
;                     QK1(8, pn0); EX2(pc1, 0, w2.x); VR1(0); SB();
;                     QK1(9, pn1); EX2(pc1, 2, w2.y); VR1(1); SB();
;                     QK1(10, pn0); EX2(pc1, 4, w2.z); VR1(2); SB();
;                     QK1(11, pn1); EX2(pc1, 6, w2.w); VR1(3); SB();
;                 } else {
;                     KR1(0); KR1(1); KR1(2); KR1(3); SB();
;                     QK1(0, negm); EX2(pc0, 0, w0.x); EX2(pc0, 2, w0.y); KR1(4); SB();
;                     QK1(1, negm); EX2(pc0, 4, w0.z); EX2(pc0, 6, w0.w); KR1(5); SB();
;                     QK1(2, pn0); EX2(pc0, 8, w1.x); EX2(pc0, 10, w1.y); KR1(6); SB();
;                     QK1(3, pn1); EX2(pc0, 12, w1.z); EX2(pc0, 14, w1.w); KR1(7); SB();
;                     QK1(4, pn0); EX2(pc1, 0, w2.x); VR1(0); SB();
;                     QK1(5, pn1); EX2(pc1, 2, w2.y); VR1(1); SB();
;                     QK1(6, pn0); EX2(pc1, 4, w2.z); VR1(2); SB();
;                     QK1(7, pn1); EX2(pc1, 6, w2.w); VR1(3); SB();
;                 }
;                 PV1(0, w0); EX2(pc1, 8, w3.x); VR1(4); SB();
;                 PV1(1, w0); EX2(pc1, 10, w3.y); VR1(5); SB();
;                 PV1(2, w1); EX2(pc1, 12, w3.z); VR1(6); SB();
;                 PV1(3, w1); EX2(pc1, 14, w3.w); VR1(7); SB();
;                 lrun += sacc;
;                 PV1(4, w2); MASK_TILE(pn0, pn1, t + 1); SB();
;                 PV1(5, w2); SB();
;                 PV1(6, w3); SB();
;                 PV1(7, w3); rmn = rowmax32(pn0, pn1); if (!USE_NEGM) rmn -= mref; SB();
;     ...
;             if (hn) { STOREK(t & 1); STOREV((t + 1) & 1); }
;             __syncthreads();
.Lmla_p9_go:
	v_exp_f32_e32 v222, v82
	v_exp_f32_e32 v223, v83
	v_add_f32_e32 v164, 0, v222
	v_cvt_pk_bf16_f32 v206, v222, v223
	v_add_f32_e32 v164, v223, v164
	v_exp_f32_e32 v224, v84
	v_exp_f32_e32 v225, v85
	v_add_f32_e32 v164, v224, v164
	v_cvt_pk_bf16_f32 v207, v224, v225
	v_add_f32_e32 v164, v225, v164
	s_waitcnt lgkmcnt(4)
	v_mfma_f32_32x32x16_bf16 v[34:49], v[182:185], v[114:117], v[66:81]
	ds_read_b128 v[198:201], v174 offset:64
	v_exp_f32_e32 v222, v86
	v_exp_f32_e32 v223, v87
	v_add_f32_e32 v164, v222, v164
	v_cvt_pk_bf16_f32 v208, v222, v223
	v_add_f32_e32 v164, v223, v164
	s_waitcnt lgkmcnt(4)
	v_mfma_f32_32x32x16_bf16 v[50:65], v[186:189], v[114:117], v[66:81]
	ds_read_b128 v[182:185], v174 offset:6720
	v_exp_f32_e32 v224, v88
	v_exp_f32_e32 v225, v89
	v_add_f32_e32 v164, v224, v164
	v_cvt_pk_bf16_f32 v209, v224, v225
	v_add_f32_e32 v164, v225, v164
	s_waitcnt lgkmcnt(3)
	v_mfma_f32_32x32x16_bf16 v[34:49], v[190:193], v[118:121], v[34:49]
	ds_read_b128 v[186:189], v174 offset:96
	v_exp_f32_e32 v222, v90
	v_exp_f32_e32 v223, v91
	v_add_f32_e32 v164, v222, v164
	v_cvt_pk_bf16_f32 v210, v222, v223
	v_add_f32_e32 v164, v223, v164
	s_waitcnt lgkmcnt(3)
	v_mfma_f32_32x32x16_bf16 v[50:65], v[194:197], v[118:121], v[50:65]
	ds_read_b128 v[190:193], v174 offset:6752
	v_exp_f32_e32 v224, v92
	v_exp_f32_e32 v225, v93
	v_add_f32_e32 v164, v224, v164
	v_cvt_pk_bf16_f32 v211, v224, v225
	v_add_f32_e32 v164, v225, v164
	s_waitcnt lgkmcnt(3)
	v_mfma_f32_32x32x16_bf16 v[34:49], v[198:201], v[122:125], v[34:49]
	ds_read_b128 v[194:197], v174 offset:128
	v_exp_f32_e32 v222, v94
	v_exp_f32_e32 v223, v95
	v_add_f32_e32 v164, v222, v164
	v_cvt_pk_bf16_f32 v212, v222, v223
	v_add_f32_e32 v164, v223, v164
	s_waitcnt lgkmcnt(3)
	v_mfma_f32_32x32x16_bf16 v[50:65], v[182:185], v[122:125], v[50:65]
	ds_read_b128 v[198:201], v174 offset:6784
	v_exp_f32_e32 v224, v96
	v_exp_f32_e32 v225, v97
	v_add_f32_e32 v164, v224, v164
	v_cvt_pk_bf16_f32 v213, v224, v225
	v_add_f32_e32 v164, v225, v164
	s_waitcnt lgkmcnt(3)
	v_mfma_f32_32x32x16_bf16 v[34:49], v[186:189], v[126:129], v[34:49]
	ds_read_b128 v[182:185], v174 offset:160
	v_exp_f32_e32 v222, v98
	v_exp_f32_e32 v223, v99
	v_add_f32_e32 v164, v222, v164
	v_cvt_pk_bf16_f32 v214, v222, v223
	v_add_f32_e32 v164, v223, v164
	s_waitcnt lgkmcnt(3)
	v_mfma_f32_32x32x16_bf16 v[50:65], v[190:193], v[126:129], v[50:65]
	ds_read_b128 v[186:189], v174 offset:6816
	v_exp_f32_e32 v224, v100
	v_exp_f32_e32 v225, v101
	v_add_f32_e32 v164, v224, v164
	v_cvt_pk_bf16_f32 v215, v224, v225
	v_add_f32_e32 v164, v225, v164
	s_waitcnt lgkmcnt(3)
	v_mfma_f32_32x32x16_bf16 v[34:49], v[194:197], v[130:133], v[34:49]
	ds_read_b128 v[190:193], v228 offset:35840
	v_exp_f32_e32 v222, v102
	v_exp_f32_e32 v223, v103
	v_add_f32_e32 v164, v222, v164
	v_cvt_pk_bf16_f32 v216, v222, v223
	v_add_f32_e32 v164, v223, v164
	s_waitcnt lgkmcnt(3)
	v_mfma_f32_32x32x16_bf16 v[50:65], v[198:201], v[130:133], v[50:65]
	ds_read_b128 v[194:197], v228 offset:40448
	v_exp_f32_e32 v224, v104
	v_exp_f32_e32 v225, v105
	v_add_f32_e32 v164, v224, v164
	v_cvt_pk_bf16_f32 v217, v224, v225
	v_add_f32_e32 v164, v225, v164
	s_waitcnt lgkmcnt(3)
	v_mfma_f32_32x32x16_bf16 v[34:49], v[182:185], v[134:137], v[34:49]
	ds_read_b128 v[198:201], v228 offset:35872
	v_exp_f32_e32 v222, v106
	v_exp_f32_e32 v223, v107
	v_add_f32_e32 v164, v222, v164
	v_cvt_pk_bf16_f32 v218, v222, v223
	v_add_f32_e32 v164, v223, v164
	s_waitcnt lgkmcnt(3)
	v_mfma_f32_32x32x16_bf16 v[50:65], v[186:189], v[134:137], v[50:65]
	ds_read_b128 v[182:185], v228 offset:40480
	v_exp_f32_e32 v224, v108
	v_exp_f32_e32 v225, v109
	v_add_f32_e32 v164, v224, v164
	v_cvt_pk_bf16_f32 v219, v224, v225
	v_add_f32_e32 v164, v225, v164
	s_waitcnt lgkmcnt(3)
	v_mfma_f32_32x32x16_bf16 v[2:17], v[190:193], v[206:209], v[2:17]
	ds_read_b128 v[186:189], v228 offset:35904
	v_exp_f32_e32 v222, v110
	v_exp_f32_e32 v223, v111
	v_add_f32_e32 v164, v222, v164
	v_cvt_pk_bf16_f32 v220, v222, v223
	v_add_f32_e32 v164, v223, v164
	s_mov_b32 s13, s20
	s_mov_b32 s20, s19
	s_add_i32 s19, s19, 1
	s_cmp_eq_u32 s19, s9
	s_cselect_b32 s19, 0, s19
	s_waitcnt lgkmcnt(3)
	v_mfma_f32_32x32x16_bf16 v[18:33], v[194:197], v[206:209], v[18:33]
	ds_read_b128 v[190:193], v228 offset:40512
	v_exp_f32_e32 v224, v112
	v_exp_f32_e32 v225, v113
	v_add_f32_e32 v164, v224, v164
	v_cvt_pk_bf16_f32 v221, v224, v225
	v_add_f32_e32 v164, v225, v164
	s_waitcnt vmcnt(2)
	ds_write_b128 v172, v[150:153] offset:58368
	v_lshl_add_u32 v222, s19, 17, v178
	global_load_dwordx4 v[150:153], v222, s[52:53]
	s_waitcnt lgkmcnt(4)
	v_mfma_f32_32x32x16_bf16 v[2:17], v[198:201], v[210:213], v[2:17]
	ds_read_b128 v[194:197], v228 offset:35936
	v_max3_f32 v224, v34, v35, v36
	v_max3_f32 v225, v50, v51, v52
	v_max3_f32 v224, v224, v37, v38
	v_max3_f32 v225, v225, v53, v54
	s_and_b64 vcc, exec, s[2:3]
	s_cbranch_vccz .Lmla_p9_nope
	ds_write_b128 v176, v[160:163] offset:58496
	v_lshl_add_u32 v222, s19, 12, v179
	global_load_dwordx4 v[160:163], v222, s[62:63]
.Lmla_p9_nope:
	s_waitcnt lgkmcnt(4)
	v_mfma_f32_32x32x16_bf16 v[18:33], v[182:185], v[210:213], v[18:33]
	ds_read_b128 v[198:201], v228 offset:40544
	ds_read_b128 v[182:185], v174 offset:22528
	v_max3_f32 v224, v224, v39, v40
	v_max3_f32 v225, v225, v55, v56
	v_max3_f32 v224, v224, v41, v42
	v_max3_f32 v225, v225, v57, v58
	v_add_u32_e32 v222, 0xb000, v173
	ds_write_b128 v222, v[202:205] offset:49152
	v_lshl_add_u32 v222, s13, 7, v168
	global_load_dwordx4 v[202:205], v222, s[56:57]
	s_waitcnt lgkmcnt(6)
	v_mfma_f32_32x32x16_bf16 v[2:17], v[186:189], v[214:217], v[2:17]
	ds_read_b128 v[186:189], v174 offset:29184
	v_max3_f32 v224, v224, v43, v44
	v_max3_f32 v225, v225, v59, v60
	v_max3_f32 v224, v224, v45, v46
	v_max3_f32 v225, v225, v61, v62
	s_waitcnt lgkmcnt(6)
	v_mfma_f32_32x32x16_bf16 v[18:33], v[190:193], v[214:217], v[18:33]
	ds_read_b128 v[190:193], v174 offset:22560
	v_max3_f32 v224, v224, v47, v48
	v_max3_f32 v225, v225, v63, v64
	v_max3_f32 v224, v224, v49, v65
	v_max_f32_e32 v224, v224, v225
	s_waitcnt lgkmcnt(5)
	v_mfma_f32_32x32x16_bf16 v[2:17], v[194:197], v[218:221], v[2:17]
	ds_read_b128 v[194:197], v174 offset:29216
	v_mov_b32_e32 v225, v224
	v_add_f32_e32 v1, v1, v164
	s_add_i32 s11, s11, 1
	v_permlane32_swap_b32_e32 v224, v225
	s_cmp_eq_u32 s9, s11
	v_max_f32_e32 v167, v224, v225
	v_cmp_lt_f32_e32 vcc, s66, v167
	s_waitcnt lgkmcnt(5)
	v_mfma_f32_32x32x16_bf16 v[18:33], v[198:201], v[218:221], v[18:33]
	s_waitcnt lgkmcnt(3)
	s_barrier

; template <int VAR>
; __device__ __forceinline__ void attn_phase(LAS unsigned char* lds, const AttnP P, int vcu, int G, int wave_s) {
;     ...
;                 if (ND0 == 6) {
;                     KR1(0); KR1(1); KR1(2); KR1(3); SB();
;                     QK1(0, negm); EX2(pc0, 0, w0.x); KR1(4); SB();
;                     QK1(1, negm); EX2(pc0, 2, w0.y); KR1(5); SB();
;                     QK1(2, pn0); EX2(pc0, 4, w0.z); KR1(6); SB();
;                     QK1(3, pn1); EX2(pc0, 6, w0.w); KR1(7); SB();
;                     QK1(4, pn0); EX2(pc0, 8, w1.x); KR1(8); SB();
;                     QK1(5, pn1); EX2(pc0, 10, w1.y); KR1(9); SB();
;                     QK1(6, pn0); EX2(pc0, 12, w1.z); KR1(10); SB();
;                     QK1(7, pn1); EX2(pc0, 14, w1.w); KR1(11); SB();
;                     QK1(8, pn0); EX2(pc1, 0, w2.x); VR1(0); SB();
;                     QK1(9, pn1); EX2(pc1, 2, w2.y); VR1(1); SB();
;                     QK1(10, pn0); EX2(pc1, 4, w2.z); VR1(2); SB();
;                     QK1(11, pn1); EX2(pc1, 6, w2.w); VR1(3); SB();
;                 } else {
;                     KR1(0); KR1(1); KR1(2); KR1(3); SB();
;                     QK1(0, negm); EX2(pc0, 0, w0.x); EX2(pc0, 2, w0.y); KR1(4); SB();
;                     QK1(1, negm); EX2(pc0, 4, w0.z); EX2(pc0, 6, w0.w); KR1(5); SB();
;                     QK1(2, pn0); EX2(pc0, 8, w1.x); EX2(pc0, 10, w1.y); KR1(6); SB();
;                     QK1(3, pn1); EX2(pc0, 12, w1.z); EX2(pc0, 14, w1.w); KR1(7); SB();
;                     QK1(4, pn0); EX2(pc1, 0, w2.x); VR1(0); SB();
;                     QK1(5, pn1); EX2(pc1, 2, w2.y); VR1(1); SB();
;                     QK1(6, pn0); EX2(pc1, 4, w2.z); VR1(2); SB();
;                     QK1(7, pn1); EX2(pc1, 6, w2.w); VR1(3); SB();
;                 }
;                 PV1(0, w0); EX2(pc1, 8, w3.x); VR1(4); SB();
;                 PV1(1, w0); EX2(pc1, 10, w3.y); VR1(5); SB();
;                 PV1(2, w1); EX2(pc1, 12, w3.z); VR1(6); SB();
;                 PV1(3, w1); EX2(pc1, 14, w3.w); VR1(7); SB();
;                 lrun += sacc;
;                 PV1(4, w2); MASK_TILE(pn0, pn1, t + 1); SB();
;                 PV1(5, w2); SB();
;                 PV1(6, w3); SB();
;                 PV1(7, w3); rmn = rowmax32(pn0, pn1); if (!USE_NEGM) rmn -= mref; SB();
;     ...
;             if (hn) { STOREK(t & 1); STOREV((t + 1) & 1); }
;             __syncthreads();
.Lmla_p11_go:
	v_exp_f32_e32 v222, v82
	v_exp_f32_e32 v223, v83
	v_add_f32_e32 v164, 0, v222
	v_cvt_pk_bf16_f32 v206, v222, v223
	v_add_f32_e32 v164, v223, v164
	v_exp_f32_e32 v224, v84
	v_exp_f32_e32 v225, v85
	v_add_f32_e32 v164, v224, v164
	v_cvt_pk_bf16_f32 v207, v224, v225
	v_add_f32_e32 v164, v225, v164
	s_waitcnt lgkmcnt(4)
	v_mfma_f32_32x32x16_bf16 v[34:49], v[182:185], v[114:117], v[66:81]
	ds_read_b128 v[198:201], v174 offset:45120
	v_exp_f32_e32 v222, v86
	v_exp_f32_e32 v223, v87
	v_add_f32_e32 v164, v222, v164
	v_cvt_pk_bf16_f32 v208, v222, v223
	v_add_f32_e32 v164, v223, v164
	s_waitcnt lgkmcnt(4)
	v_mfma_f32_32x32x16_bf16 v[50:65], v[186:189], v[114:117], v[66:81]
	ds_read_b128 v[182:185], v174 offset:51776
	v_exp_f32_e32 v224, v88
	v_exp_f32_e32 v225, v89
	v_add_f32_e32 v164, v224, v164
	v_cvt_pk_bf16_f32 v209, v224, v225
	v_add_f32_e32 v164, v225, v164
	s_waitcnt lgkmcnt(3)
	v_mfma_f32_32x32x16_bf16 v[34:49], v[190:193], v[118:121], v[34:49]
	ds_read_b128 v[186:189], v174 offset:45152
	v_exp_f32_e32 v222, v90
	v_exp_f32_e32 v223, v91
	v_add_f32_e32 v164, v222, v164
	v_cvt_pk_bf16_f32 v210, v222, v223
	v_add_f32_e32 v164, v223, v164
	s_waitcnt lgkmcnt(3)
	v_mfma_f32_32x32x16_bf16 v[50:65], v[194:197], v[118:121], v[50:65]
	ds_read_b128 v[190:193], v174 offset:51808
	v_exp_f32_e32 v224, v92
	v_exp_f32_e32 v225, v93
	v_add_f32_e32 v164, v224, v164
	v_cvt_pk_bf16_f32 v211, v224, v225
	v_add_f32_e32 v164, v225, v164
	s_waitcnt lgkmcnt(3)
	v_mfma_f32_32x32x16_bf16 v[34:49], v[198:201], v[122:125], v[34:49]
	ds_read_b128 v[194:197], v174 offset:45184
	v_exp_f32_e32 v222, v94
	v_exp_f32_e32 v223, v95
	v_add_f32_e32 v164, v222, v164
	v_cvt_pk_bf16_f32 v212, v222, v223
	v_add_f32_e32 v164, v223, v164
	s_waitcnt lgkmcnt(3)
	v_mfma_f32_32x32x16_bf16 v[50:65], v[182:185], v[122:125], v[50:65]
	ds_read_b128 v[198:201], v174 offset:51840
	v_exp_f32_e32 v224, v96
	v_exp_f32_e32 v225, v97
	v_add_f32_e32 v164, v224, v164
	v_cvt_pk_bf16_f32 v213, v224, v225
	v_add_f32_e32 v164, v225, v164
	s_waitcnt lgkmcnt(3)
	v_mfma_f32_32x32x16_bf16 v[34:49], v[186:189], v[126:129], v[34:49]
	ds_read_b128 v[182:185], v174 offset:45216
	v_exp_f32_e32 v222, v98
	v_exp_f32_e32 v223, v99
	v_add_f32_e32 v164, v222, v164
	v_cvt_pk_bf16_f32 v214, v222, v223
	v_add_f32_e32 v164, v223, v164
	s_waitcnt lgkmcnt(3)
	v_mfma_f32_32x32x16_bf16 v[50:65], v[190:193], v[126:129], v[50:65]
	ds_read_b128 v[186:189], v174 offset:51872
	v_exp_f32_e32 v224, v100
	v_exp_f32_e32 v225, v101
	v_add_f32_e32 v164, v224, v164
	v_cvt_pk_bf16_f32 v215, v224, v225
	v_add_f32_e32 v164, v225, v164
	s_waitcnt lgkmcnt(3)
	v_mfma_f32_32x32x16_bf16 v[34:49], v[194:197], v[130:133], v[34:49]
	ds_read_b128 v[190:193], v181 offset:49152
	v_exp_f32_e32 v222, v102
	v_exp_f32_e32 v223, v103
	v_add_f32_e32 v164, v222, v164
	v_cvt_pk_bf16_f32 v216, v222, v223
	v_add_f32_e32 v164, v223, v164
	s_waitcnt lgkmcnt(3)
	v_mfma_f32_32x32x16_bf16 v[50:65], v[198:201], v[130:133], v[50:65]
	ds_read_b128 v[194:197], v181 offset:53760
	v_exp_f32_e32 v224, v104
	v_exp_f32_e32 v225, v105
	v_add_f32_e32 v164, v224, v164
	v_cvt_pk_bf16_f32 v217, v224, v225
	v_add_f32_e32 v164, v225, v164
	s_waitcnt lgkmcnt(3)
	v_mfma_f32_32x32x16_bf16 v[34:49], v[182:185], v[134:137], v[34:49]
	ds_read_b128 v[198:201], v181 offset:49184
	v_exp_f32_e32 v222, v106
	v_exp_f32_e32 v223, v107
	v_add_f32_e32 v164, v222, v164
	v_cvt_pk_bf16_f32 v218, v222, v223
	v_add_f32_e32 v164, v223, v164
	s_waitcnt lgkmcnt(3)
	v_mfma_f32_32x32x16_bf16 v[50:65], v[186:189], v[134:137], v[50:65]
	ds_read_b128 v[182:185], v181 offset:53792
	v_exp_f32_e32 v224, v108
	v_exp_f32_e32 v225, v109
	v_add_f32_e32 v164, v224, v164
	v_cvt_pk_bf16_f32 v219, v224, v225
	v_add_f32_e32 v164, v225, v164
	s_waitcnt lgkmcnt(3)
	v_mfma_f32_32x32x16_bf16 v[2:17], v[190:193], v[206:209], v[2:17]
	ds_read_b128 v[186:189], v181 offset:49216
	v_exp_f32_e32 v222, v110
	v_exp_f32_e32 v223, v111
	v_add_f32_e32 v164, v222, v164
	v_cvt_pk_bf16_f32 v220, v222, v223
	v_add_f32_e32 v164, v223, v164
	s_mov_b32 s13, s20
	s_mov_b32 s20, s19
	s_add_i32 s19, s19, 1
	s_cmp_eq_u32 s19, s9
	s_cselect_b32 s19, 0, s19
	s_waitcnt lgkmcnt(3)
	v_mfma_f32_32x32x16_bf16 v[18:33], v[194:197], v[206:209], v[18:33]
	ds_read_b128 v[190:193], v181 offset:53824
	v_exp_f32_e32 v224, v112
	v_exp_f32_e32 v225, v113
	v_add_f32_e32 v164, v224, v164
	v_cvt_pk_bf16_f32 v221, v224, v225
	v_add_f32_e32 v164, v225, v164
	s_waitcnt vmcnt(2)
	ds_write_b128 v172, v[150:153]
	v_lshl_add_u32 v222, s19, 17, v178
	global_load_dwordx4 v[150:153], v222, s[52:53]
	s_waitcnt lgkmcnt(4)
	v_mfma_f32_32x32x16_bf16 v[2:17], v[198:201], v[210:213], v[2:17]
	ds_read_b128 v[194:197], v181 offset:49248
	v_max3_f32 v224, v34, v35, v36
	v_max3_f32 v225, v50, v51, v52
	v_max3_f32 v224, v224, v37, v38
	v_max3_f32 v225, v225, v53, v54
	s_and_b64 vcc, exec, s[2:3]
	s_cbranch_vccz .Lmla_p11_nope
	ds_write_b128 v176, v[160:163] offset:128
	v_lshl_add_u32 v222, s19, 12, v179
	global_load_dwordx4 v[160:163], v222, s[62:63]
.Lmla_p11_nope:
	s_waitcnt lgkmcnt(4)
	v_mfma_f32_32x32x16_bf16 v[18:33], v[182:185], v[210:213], v[18:33]
	ds_read_b128 v[198:201], v181 offset:53856
	ds_read_b128 v[182:185], v229 offset:13312
	v_max3_f32 v224, v224, v39, v40
	v_max3_f32 v225, v225, v55, v56
	v_max3_f32 v224, v224, v41, v42
	v_max3_f32 v225, v225, v57, v58
	ds_write_b128 v173, v[202:205] offset:35840
	v_lshl_add_u32 v222, s13, 7, v168
	global_load_dwordx4 v[202:205], v222, s[56:57]
	s_waitcnt lgkmcnt(6)
	v_mfma_f32_32x32x16_bf16 v[2:17], v[186:189], v[214:217], v[2:17]
	ds_read_b128 v[186:189], v229 offset:19968
	v_max3_f32 v224, v224, v43, v44
	v_max3_f32 v225, v225, v59, v60
	v_max3_f32 v224, v224, v45, v46
	v_max3_f32 v225, v225, v61, v62
	s_waitcnt lgkmcnt(6)
	v_mfma_f32_32x32x16_bf16 v[18:33], v[190:193], v[214:217], v[18:33]
	ds_read_b128 v[190:193], v229 offset:13344
	v_max3_f32 v224, v224, v47, v48
	v_max3_f32 v225, v225, v63, v64
	v_max3_f32 v224, v224, v49, v65
	v_max_f32_e32 v224, v224, v225
	s_waitcnt lgkmcnt(5)
	v_mfma_f32_32x32x16_bf16 v[2:17], v[194:197], v[218:221], v[2:17]
	ds_read_b128 v[194:197], v229 offset:20000
	v_mov_b32_e32 v225, v224
	v_add_f32_e32 v1, v1, v164
	s_add_i32 s11, s11, 1
	v_permlane32_swap_b32_e32 v224, v225
	s_cmp_eq_u32 s9, s11
	v_max_f32_e32 v167, v224, v225
	v_cmp_lt_f32_e32 vcc, s66, v167
	s_waitcnt lgkmcnt(5)
	v_mfma_f32_32x32x16_bf16 v[18:33], v[198:201], v[218:221], v[18:33]
	s_waitcnt lgkmcnt(3)
	s_barrier

; template <int VAR>
; __device__ __forceinline__ void attn_phase(LAS unsigned char* lds, const AttnP P, int vcu, int G, int wave_s) {
;     ...
;                 if (ND0 == 6) {
;                     KR1(0); KR1(1); KR1(2); KR1(3); SB();
;                     QK1(0, negm); EX2(pc0, 0, w0.x); KR1(4); SB();
;                     QK1(1, negm); EX2(pc0, 2, w0.y); KR1(5); SB();
;                     QK1(2, pn0); EX2(pc0, 4, w0.z); KR1(6); SB();
;                     QK1(3, pn1); EX2(pc0, 6, w0.w); KR1(7); SB();
;                     QK1(4, pn0); EX2(pc0, 8, w1.x); KR1(8); SB();
;                     QK1(5, pn1); EX2(pc0, 10, w1.y); KR1(9); SB();
;                     QK1(6, pn0); EX2(pc0, 12, w1.z); KR1(10); SB();
;                     QK1(7, pn1); EX2(pc0, 14, w1.w); KR1(11); SB();
;                     QK1(8, pn0); EX2(pc1, 0, w2.x); VR1(0); SB();
;                     QK1(9, pn1); EX2(pc1, 2, w2.y); VR1(1); SB();
;                     QK1(10, pn0); EX2(pc1, 4, w2.z); VR1(2); SB();
;                     QK1(11, pn1); EX2(pc1, 6, w2.w); VR1(3); SB();
;                 } else {
;                     KR1(0); KR1(1); KR1(2); KR1(3); SB();
;                     QK1(0, negm); EX2(pc0, 0, w0.x); EX2(pc0, 2, w0.y); KR1(4); SB();
;                     QK1(1, negm); EX2(pc0, 4, w0.z); EX2(pc0, 6, w0.w); KR1(5); SB();
;                     QK1(2, pn0); EX2(pc0, 8, w1.x); EX2(pc0, 10, w1.y); KR1(6); SB();
;                     QK1(3, pn1); EX2(pc0, 12, w1.z); EX2(pc0, 14, w1.w); KR1(7); SB();
;                     QK1(4, pn0); EX2(pc1, 0, w2.x); VR1(0); SB();
;                     QK1(5, pn1); EX2(pc1, 2, w2.y); VR1(1); SB();
;                     QK1(6, pn0); EX2(pc1, 4, w2.z); VR1(2); SB();
;                     QK1(7, pn1); EX2(pc1, 6, w2.w); VR1(3); SB();
;                 }
;                 PV1(0, w0); EX2(pc1, 8, w3.x); VR1(4); SB();
;                 PV1(1, w0); EX2(pc1, 10, w3.y); VR1(5); SB();
;                 PV1(2, w1); EX2(pc1, 12, w3.z); VR1(6); SB();
;                 PV1(3, w1); EX2(pc1, 14, w3.w); VR1(7); SB();
;                 lrun += sacc;
;                 PV1(4, w2); MASK_TILE(pn0, pn1, t + 1); SB();
;                 PV1(5, w2); SB();
;                 PV1(6, w3); SB();
;                 PV1(7, w3); rmn = rowmax32(pn0, pn1); if (!USE_NEGM) rmn -= mref; SB();
;     ...
;             if (hn) { STOREK(t & 1); STOREV((t + 1) & 1); }
;             __syncthreads();
.Lmla_p13_go:
	v_exp_f32_e32 v222, v82
	v_exp_f32_e32 v223, v83
	v_add_f32_e32 v164, 0, v222
	v_cvt_pk_bf16_f32 v206, v222, v223
	v_add_f32_e32 v164, v223, v164
	v_exp_f32_e32 v224, v84
	v_exp_f32_e32 v225, v85
	v_add_f32_e32 v164, v224, v164
	v_cvt_pk_bf16_f32 v207, v224, v225
	v_add_f32_e32 v164, v225, v164
	s_waitcnt lgkmcnt(4)
	v_mfma_f32_32x32x16_bf16 v[34:49], v[182:185], v[114:117], v[66:81]
	ds_read_b128 v[198:201], v229 offset:26688
	v_exp_f32_e32 v222, v86
	v_exp_f32_e32 v223, v87
	v_add_f32_e32 v164, v222, v164
	v_cvt_pk_bf16_f32 v208, v222, v223
	v_add_f32_e32 v164, v223, v164
	s_waitcnt lgkmcnt(4)
	v_mfma_f32_32x32x16_bf16 v[50:65], v[186:189], v[114:117], v[66:81]
	ds_read_b128 v[182:185], v229 offset:33344
	v_exp_f32_e32 v224, v88
	v_exp_f32_e32 v225, v89
	v_add_f32_e32 v164, v224, v164
	v_cvt_pk_bf16_f32 v209, v224, v225
	v_add_f32_e32 v164, v225, v164
	s_waitcnt lgkmcnt(3)
	v_mfma_f32_32x32x16_bf16 v[34:49], v[190:193], v[118:121], v[34:49]
	ds_read_b128 v[186:189], v229 offset:26720
	v_exp_f32_e32 v222, v90
	v_exp_f32_e32 v223, v91
	v_add_f32_e32 v164, v222, v164
	v_cvt_pk_bf16_f32 v210, v222, v223
	v_add_f32_e32 v164, v223, v164
	s_waitcnt lgkmcnt(3)
	v_mfma_f32_32x32x16_bf16 v[50:65], v[194:197], v[118:121], v[50:65]
	ds_read_b128 v[190:193], v229 offset:33376
	v_exp_f32_e32 v224, v92
	v_exp_f32_e32 v225, v93
	v_add_f32_e32 v164, v224, v164
	v_cvt_pk_bf16_f32 v211, v224, v225
	v_add_f32_e32 v164, v225, v164
	s_waitcnt lgkmcnt(3)
	v_mfma_f32_32x32x16_bf16 v[34:49], v[198:201], v[122:125], v[34:49]
	ds_read_b128 v[194:197], v229 offset:26752
	v_exp_f32_e32 v222, v94
	v_exp_f32_e32 v223, v95
	v_add_f32_e32 v164, v222, v164
	v_cvt_pk_bf16_f32 v212, v222, v223
	v_add_f32_e32 v164, v223, v164
	s_waitcnt lgkmcnt(3)
	v_mfma_f32_32x32x16_bf16 v[50:65], v[182:185], v[122:125], v[50:65]
	ds_read_b128 v[198:201], v229 offset:33408
	v_exp_f32_e32 v224, v96
	v_exp_f32_e32 v225, v97
	v_add_f32_e32 v164, v224, v164
	v_cvt_pk_bf16_f32 v213, v224, v225
	v_add_f32_e32 v164, v225, v164
	s_waitcnt lgkmcnt(3)
	v_mfma_f32_32x32x16_bf16 v[34:49], v[186:189], v[126:129], v[34:49]
	ds_read_b128 v[182:185], v229 offset:26784
	v_exp_f32_e32 v222, v98
	v_exp_f32_e32 v223, v99
	v_add_f32_e32 v164, v222, v164
	v_cvt_pk_bf16_f32 v214, v222, v223
	v_add_f32_e32 v164, v223, v164
	s_waitcnt lgkmcnt(3)
	v_mfma_f32_32x32x16_bf16 v[50:65], v[190:193], v[126:129], v[50:65]
	ds_read_b128 v[186:189], v229 offset:33440
	v_exp_f32_e32 v224, v100
	v_exp_f32_e32 v225, v101
	v_add_f32_e32 v164, v224, v164
	v_cvt_pk_bf16_f32 v215, v224, v225
	v_add_f32_e32 v164, v225, v164
	s_waitcnt lgkmcnt(3)
	v_mfma_f32_32x32x16_bf16 v[34:49], v[194:197], v[130:133], v[34:49]
	ds_read_b128 v[190:193], v228 offset:35840
	v_exp_f32_e32 v222, v102
	v_exp_f32_e32 v223, v103
	v_add_f32_e32 v164, v222, v164
	v_cvt_pk_bf16_f32 v216, v222, v223
	v_add_f32_e32 v164, v223, v164
	s_waitcnt lgkmcnt(3)
	v_mfma_f32_32x32x16_bf16 v[50:65], v[198:201], v[130:133], v[50:65]
	ds_read_b128 v[194:197], v228 offset:40448
	v_exp_f32_e32 v224, v104
	v_exp_f32_e32 v225, v105
	v_add_f32_e32 v164, v224, v164
	v_cvt_pk_bf16_f32 v217, v224, v225
	v_add_f32_e32 v164, v225, v164
	s_waitcnt lgkmcnt(3)
	v_mfma_f32_32x32x16_bf16 v[34:49], v[182:185], v[134:137], v[34:49]
	ds_read_b128 v[198:201], v228 offset:35872
	v_exp_f32_e32 v222, v106
	v_exp_f32_e32 v223, v107
	v_add_f32_e32 v164, v222, v164
	v_cvt_pk_bf16_f32 v218, v222, v223
	v_add_f32_e32 v164, v223, v164
	s_waitcnt lgkmcnt(3)
	v_mfma_f32_32x32x16_bf16 v[50:65], v[186:189], v[134:137], v[50:65]
	ds_read_b128 v[182:185], v228 offset:40480
	v_exp_f32_e32 v224, v108
	v_exp_f32_e32 v225, v109
	v_add_f32_e32 v164, v224, v164
	v_cvt_pk_bf16_f32 v219, v224, v225
	v_add_f32_e32 v164, v225, v164
	s_waitcnt lgkmcnt(3)
	v_mfma_f32_32x32x16_bf16 v[2:17], v[190:193], v[206:209], v[2:17]
	ds_read_b128 v[186:189], v228 offset:35904
	v_exp_f32_e32 v222, v110
	v_exp_f32_e32 v223, v111
	v_add_f32_e32 v164, v222, v164
	v_cvt_pk_bf16_f32 v220, v222, v223
	v_add_f32_e32 v164, v223, v164
	s_mov_b32 s13, s20
	s_mov_b32 s20, s19
	s_add_i32 s19, s19, 1
	s_cmp_eq_u32 s19, s9
	s_cselect_b32 s19, 0, s19
	s_waitcnt lgkmcnt(3)
	v_mfma_f32_32x32x16_bf16 v[18:33], v[194:197], v[206:209], v[18:33]
	ds_read_b128 v[190:193], v228 offset:40512
	v_exp_f32_e32 v224, v112
	v_exp_f32_e32 v225, v113
	v_add_f32_e32 v164, v224, v164
	v_cvt_pk_bf16_f32 v221, v224, v225
	v_add_f32_e32 v164, v225, v164
	s_waitcnt vmcnt(2)
	ds_write_b128 v172, v[150:153] offset:45056
	v_lshl_add_u32 v222, s19, 17, v178
	global_load_dwordx4 v[150:153], v222, s[52:53]
	s_waitcnt lgkmcnt(4)
	v_mfma_f32_32x32x16_bf16 v[2:17], v[198:201], v[210:213], v[2:17]
	ds_read_b128 v[194:197], v228 offset:35936
	v_max3_f32 v224, v34, v35, v36
	v_max3_f32 v225, v50, v51, v52
	v_max3_f32 v224, v224, v37, v38
	v_max3_f32 v225, v225, v53, v54
	s_and_b64 vcc, exec, s[2:3]
	s_cbranch_vccz .Lmla_p13_nope
	ds_write_b128 v176, v[160:163] offset:45184
	v_lshl_add_u32 v222, s19, 12, v179
	global_load_dwordx4 v[160:163], v222, s[62:63]
.Lmla_p13_nope:
	s_waitcnt lgkmcnt(4)
	v_mfma_f32_32x32x16_bf16 v[18:33], v[182:185], v[210:213], v[18:33]
	ds_read_b128 v[198:201], v228 offset:40544
	ds_read_b128 v[182:185], v174
	v_max3_f32 v224, v224, v39, v40
	v_max3_f32 v225, v225, v55, v56
	v_max3_f32 v224, v224, v41, v42
	v_max3_f32 v225, v225, v57, v58
	v_add_u32_e32 v222, 0xb000, v173
	ds_write_b128 v222, v[202:205] offset:49152
	v_lshl_add_u32 v222, s13, 7, v168
	global_load_dwordx4 v[202:205], v222, s[56:57]
	s_waitcnt lgkmcnt(6)
	v_mfma_f32_32x32x16_bf16 v[2:17], v[186:189], v[214:217], v[2:17]
	ds_read_b128 v[186:189], v174 offset:6656
	v_max3_f32 v224, v224, v43, v44
	v_max3_f32 v225, v225, v59, v60
	v_max3_f32 v224, v224, v45, v46
	v_max3_f32 v225, v225, v61, v62
	s_waitcnt lgkmcnt(6)
	v_mfma_f32_32x32x16_bf16 v[18:33], v[190:193], v[214:217], v[18:33]
	ds_read_b128 v[190:193], v174 offset:32
	v_max3_f32 v224, v224, v47, v48
	v_max3_f32 v225, v225, v63, v64
	v_max3_f32 v224, v224, v49, v65
	v_max_f32_e32 v224, v224, v225
	s_waitcnt lgkmcnt(5)
	v_mfma_f32_32x32x16_bf16 v[2:17], v[194:197], v[218:221], v[2:17]
	ds_read_b128 v[194:197], v174 offset:6688
	v_mov_b32_e32 v225, v224
	v_add_f32_e32 v1, v1, v164
	s_add_i32 s11, s11, 1
	v_permlane32_swap_b32_e32 v224, v225
	s_cmp_eq_u32 s9, s11
	v_max_f32_e32 v167, v224, v225
	v_cmp_lt_f32_e32 vcc, s66, v167
	s_waitcnt lgkmcnt(5)
	v_mfma_f32_32x32x16_bf16 v[18:33], v[198:201], v[218:221], v[18:33]
	s_waitcnt lgkmcnt(3)
	s_barrier

; template <int VAR>
; __device__ __forceinline__ void attn_phase(LAS unsigned char* lds, const AttnP P, int vcu, int G, int wave_s) {
;     ...
;                 if (ND0 == 6) {
;                     KR1(0); KR1(1); KR1(2); KR1(3); SB();
;                     QK1(0, negm); EX2(pc0, 0, w0.x); KR1(4); SB();
;                     QK1(1, negm); EX2(pc0, 2, w0.y); KR1(5); SB();
;                     QK1(2, pn0); EX2(pc0, 4, w0.z); KR1(6); SB();
;                     QK1(3, pn1); EX2(pc0, 6, w0.w); KR1(7); SB();
;                     QK1(4, pn0); EX2(pc0, 8, w1.x); KR1(8); SB();
;                     QK1(5, pn1); EX2(pc0, 10, w1.y); KR1(9); SB();
;                     QK1(6, pn0); EX2(pc0, 12, w1.z); KR1(10); SB();
;                     QK1(7, pn1); EX2(pc0, 14, w1.w); KR1(11); SB();
;                     QK1(8, pn0); EX2(pc1, 0, w2.x); VR1(0); SB();
;                     QK1(9, pn1); EX2(pc1, 2, w2.y); VR1(1); SB();
;                     QK1(10, pn0); EX2(pc1, 4, w2.z); VR1(2); SB();
;                     QK1(11, pn1); EX2(pc1, 6, w2.w); VR1(3); SB();
;                 } else {
;                     KR1(0); KR1(1); KR1(2); KR1(3); SB();
;                     QK1(0, negm); EX2(pc0, 0, w0.x); EX2(pc0, 2, w0.y); KR1(4); SB();
;                     QK1(1, negm); EX2(pc0, 4, w0.z); EX2(pc0, 6, w0.w); KR1(5); SB();
;                     QK1(2, pn0); EX2(pc0, 8, w1.x); EX2(pc0, 10, w1.y); KR1(6); SB();
;                     QK1(3, pn1); EX2(pc0, 12, w1.z); EX2(pc0, 14, w1.w); KR1(7); SB();
;                     QK1(4, pn0); EX2(pc1, 0, w2.x); VR1(0); SB();
;                     QK1(5, pn1); EX2(pc1, 2, w2.y); VR1(1); SB();
;                     QK1(6, pn0); EX2(pc1, 4, w2.z); VR1(2); SB();
;                     QK1(7, pn1); EX2(pc1, 6, w2.w); VR1(3); SB();
;                 }
;                 PV1(0, w0); EX2(pc1, 8, w3.x); VR1(4); SB();
;                 PV1(1, w0); EX2(pc1, 10, w3.y); VR1(5); SB();
;                 PV1(2, w1); EX2(pc1, 12, w3.z); VR1(6); SB();
;                 PV1(3, w1); EX2(pc1, 14, w3.w); VR1(7); SB();
;                 lrun += sacc;
;                 PV1(4, w2); MASK_TILE(pn0, pn1, t + 1); SB();
;                 PV1(5, w2); SB();
;                 PV1(6, w3); SB();
;                 PV1(7, w3); rmn = rowmax32(pn0, pn1); if (!USE_NEGM) rmn -= mref; SB();
;     ...
;             if (hn) { STOREK(t & 1); STOREV((t + 1) & 1); }
;             __syncthreads();
.Lmla_p15_go:
	v_exp_f32_e32 v222, v82
	v_exp_f32_e32 v223, v83
	v_add_f32_e32 v164, 0, v222
	v_cvt_pk_bf16_f32 v206, v222, v223
	v_add_f32_e32 v164, v223, v164
	v_exp_f32_e32 v224, v84
	v_exp_f32_e32 v225, v85
	v_add_f32_e32 v164, v224, v164
	v_cvt_pk_bf16_f32 v207, v224, v225
	v_add_f32_e32 v164, v225, v164
	s_waitcnt lgkmcnt(4)
	v_mfma_f32_32x32x16_bf16 v[34:49], v[182:185], v[114:117], v[66:81]
	ds_read_b128 v[198:201], v174 offset:22592
	v_exp_f32_e32 v222, v86
	v_exp_f32_e32 v223, v87
	v_add_f32_e32 v164, v222, v164
	v_cvt_pk_bf16_f32 v208, v222, v223
	v_add_f32_e32 v164, v223, v164
	s_waitcnt lgkmcnt(4)
	v_mfma_f32_32x32x16_bf16 v[50:65], v[186:189], v[114:117], v[66:81]
	ds_read_b128 v[182:185], v174 offset:29248
	v_exp_f32_e32 v224, v88
	v_exp_f32_e32 v225, v89
	v_add_f32_e32 v164, v224, v164
	v_cvt_pk_bf16_f32 v209, v224, v225
	v_add_f32_e32 v164, v225, v164
	s_waitcnt lgkmcnt(3)
	v_mfma_f32_32x32x16_bf16 v[34:49], v[190:193], v[118:121], v[34:49]
	ds_read_b128 v[186:189], v174 offset:22624
	v_exp_f32_e32 v222, v90
	v_exp_f32_e32 v223, v91
	v_add_f32_e32 v164, v222, v164
	v_cvt_pk_bf16_f32 v210, v222, v223
	v_add_f32_e32 v164, v223, v164
	s_waitcnt lgkmcnt(3)
	v_mfma_f32_32x32x16_bf16 v[50:65], v[194:197], v[118:121], v[50:65]
	ds_read_b128 v[190:193], v174 offset:29280
	v_exp_f32_e32 v224, v92
	v_exp_f32_e32 v225, v93
	v_add_f32_e32 v164, v224, v164
	v_cvt_pk_bf16_f32 v211, v224, v225
	v_add_f32_e32 v164, v225, v164
	s_waitcnt lgkmcnt(3)
	v_mfma_f32_32x32x16_bf16 v[34:49], v[198:201], v[122:125], v[34:49]
	ds_read_b128 v[194:197], v174 offset:22656
	v_exp_f32_e32 v222, v94
	v_exp_f32_e32 v223, v95
	v_add_f32_e32 v164, v222, v164
	v_cvt_pk_bf16_f32 v212, v222, v223
	v_add_f32_e32 v164, v223, v164
	s_waitcnt lgkmcnt(3)
	v_mfma_f32_32x32x16_bf16 v[50:65], v[182:185], v[122:125], v[50:65]
	ds_read_b128 v[198:201], v174 offset:29312
	v_exp_f32_e32 v224, v96
	v_exp_f32_e32 v225, v97
	v_add_f32_e32 v164, v224, v164
	v_cvt_pk_bf16_f32 v213, v224, v225
	v_add_f32_e32 v164, v225, v164
	s_waitcnt lgkmcnt(3)
	v_mfma_f32_32x32x16_bf16 v[34:49], v[186:189], v[126:129], v[34:49]
	ds_read_b128 v[182:185], v174 offset:22688
	v_exp_f32_e32 v222, v98
	v_exp_f32_e32 v223, v99
	v_add_f32_e32 v164, v222, v164
	v_cvt_pk_bf16_f32 v214, v222, v223
	v_add_f32_e32 v164, v223, v164
	s_waitcnt lgkmcnt(3)
	v_mfma_f32_32x32x16_bf16 v[50:65], v[190:193], v[126:129], v[50:65]
	ds_read_b128 v[186:189], v174 offset:29344
	v_exp_f32_e32 v224, v100
	v_exp_f32_e32 v225, v101
	v_add_f32_e32 v164, v224, v164
	v_cvt_pk_bf16_f32 v215, v224, v225
	v_add_f32_e32 v164, v225, v164
	s_waitcnt lgkmcnt(3)
	v_mfma_f32_32x32x16_bf16 v[34:49], v[194:197], v[130:133], v[34:49]
	ds_read_b128 v[190:193], v181 offset:49152
	v_exp_f32_e32 v222, v102
	v_exp_f32_e32 v223, v103
	v_add_f32_e32 v164, v222, v164
	v_cvt_pk_bf16_f32 v216, v222, v223
	v_add_f32_e32 v164, v223, v164
	s_waitcnt lgkmcnt(3)
	v_mfma_f32_32x32x16_bf16 v[50:65], v[198:201], v[130:133], v[50:65]
	ds_read_b128 v[194:197], v181 offset:53760
	v_exp_f32_e32 v224, v104
	v_exp_f32_e32 v225, v105
	v_add_f32_e32 v164, v224, v164
	v_cvt_pk_bf16_f32 v217, v224, v225
	v_add_f32_e32 v164, v225, v164
	s_waitcnt lgkmcnt(3)
	v_mfma_f32_32x32x16_bf16 v[34:49], v[182:185], v[134:137], v[34:49]
	ds_read_b128 v[198:201], v181 offset:49184
	v_exp_f32_e32 v222, v106
	v_exp_f32_e32 v223, v107
	v_add_f32_e32 v164, v222, v164
	v_cvt_pk_bf16_f32 v218, v222, v223
	v_add_f32_e32 v164, v223, v164
	s_waitcnt lgkmcnt(3)
	v_mfma_f32_32x32x16_bf16 v[50:65], v[186:189], v[134:137], v[50:65]
	ds_read_b128 v[182:185], v181 offset:53792
	v_exp_f32_e32 v224, v108
	v_exp_f32_e32 v225, v109
	v_add_f32_e32 v164, v224, v164
	v_cvt_pk_bf16_f32 v219, v224, v225
	v_add_f32_e32 v164, v225, v164
	s_waitcnt lgkmcnt(3)
	v_mfma_f32_32x32x16_bf16 v[2:17], v[190:193], v[206:209], v[2:17]
	ds_read_b128 v[186:189], v181 offset:49216
	v_exp_f32_e32 v222, v110
	v_exp_f32_e32 v223, v111
	v_add_f32_e32 v164, v222, v164
	v_cvt_pk_bf16_f32 v220, v222, v223
	v_add_f32_e32 v164, v223, v164
	s_mov_b32 s13, s20
	s_mov_b32 s20, s19
	s_add_i32 s19, s19, 1
	s_cmp_eq_u32 s19, s9
	s_cselect_b32 s19, 0, s19
	s_waitcnt lgkmcnt(3)
	v_mfma_f32_32x32x16_bf16 v[18:33], v[194:197], v[206:209], v[18:33]
	ds_read_b128 v[190:193], v181 offset:53824
	v_exp_f32_e32 v224, v112
	v_exp_f32_e32 v225, v113
	v_add_f32_e32 v164, v224, v164
	v_cvt_pk_bf16_f32 v221, v224, v225
	v_add_f32_e32 v164, v225, v164
	s_waitcnt vmcnt(2)
	v_add_u32_e32 v222, 0xb000, v172
	ds_write_b128 v222, v[150:153] offset:26624
	v_lshl_add_u32 v222, s19, 17, v178
	global_load_dwordx4 v[150:153], v222, s[52:53]
	s_waitcnt lgkmcnt(4)
	v_mfma_f32_32x32x16_bf16 v[2:17], v[198:201], v[210:213], v[2:17]
	ds_read_b128 v[194:197], v181 offset:49248
	v_max3_f32 v224, v34, v35, v36
	v_max3_f32 v225, v50, v51, v52
	v_max3_f32 v224, v224, v37, v38
	v_max3_f32 v225, v225, v53, v54
	s_and_b64 vcc, exec, s[2:3]
	s_cbranch_vccz .Lmla_p15_nope
	v_add_u32_e32 v222, 0xb000, v176
	ds_write_b128 v222, v[160:163] offset:26752
	v_lshl_add_u32 v222, s19, 12, v179
	global_load_dwordx4 v[160:163], v222, s[62:63]
.Lmla_p15_nope:
	s_waitcnt lgkmcnt(4)
	v_mfma_f32_32x32x16_bf16 v[18:33], v[182:185], v[210:213], v[18:33]
	ds_read_b128 v[198:201], v181 offset:53856
	ds_read_b128 v[182:185], v174 offset:45056
	v_max3_f32 v224, v224, v39, v40
	v_max3_f32 v225, v225, v55, v56
	v_max3_f32 v224, v224, v41, v42
	v_max3_f32 v225, v225, v57, v58
	ds_write_b128 v173, v[202:205] offset:35840
	v_lshl_add_u32 v222, s13, 7, v168
	global_load_dwordx4 v[202:205], v222, s[56:57]
	s_waitcnt lgkmcnt(6)
	v_mfma_f32_32x32x16_bf16 v[2:17], v[186:189], v[214:217], v[2:17]
	ds_read_b128 v[186:189], v174 offset:51712
	v_max3_f32 v224, v224, v43, v44
	v_max3_f32 v225, v225, v59, v60
	v_max3_f32 v224, v224, v45, v46
	v_max3_f32 v225, v225, v61, v62
	s_waitcnt lgkmcnt(6)
	v_mfma_f32_32x32x16_bf16 v[18:33], v[190:193], v[214:217], v[18:33]
	ds_read_b128 v[190:193], v174 offset:45088
	v_max3_f32 v224, v224, v47, v48
	v_max3_f32 v225, v225, v63, v64
	v_max3_f32 v224, v224, v49, v65
	v_max_f32_e32 v224, v224, v225
	s_waitcnt lgkmcnt(5)
	v_mfma_f32_32x32x16_bf16 v[2:17], v[194:197], v[218:221], v[2:17]
	ds_read_b128 v[194:197], v174 offset:51744
	v_mov_b32_e32 v225, v224
	v_add_f32_e32 v1, v1, v164
	s_add_i32 s11, s11, 1
	v_permlane32_swap_b32_e32 v224, v225
	s_cmp_eq_u32 s9, s11
	v_max_f32_e32 v167, v224, v225
	v_cmp_lt_f32_e32 vcc, s66, v167
	s_waitcnt lgkmcnt(5)
	v_mfma_f32_32x32x16_bf16 v[18:33], v[198:201], v[218:221], v[18:33]
	s_waitcnt lgkmcnt(3)
	s_barrier

; #define SB() __builtin_amdgcn_sched_barrier(0)
; template <int VAR>
; __device__ __forceinline__ void attn_phase(LAS unsigned char* lds, const AttnP P, int vcu, int G, int wave_s) {
;     ...
;                 if (ND0 == 6) {
;                     KR1(0); KR1(1); KR1(2); KR1(3); SB();
;                     QK1(0, negm); EX2(pc0, 0, w0.x); KR1(4); SB();
;                     QK1(1, negm); EX2(pc0, 2, w0.y); KR1(5); SB();
;                     QK1(2, pn0); EX2(pc0, 4, w0.z); KR1(6); SB();
;                     QK1(3, pn1); EX2(pc0, 6, w0.w); KR1(7); SB();
;                     QK1(4, pn0); EX2(pc0, 8, w1.x); KR1(8); SB();
;                     QK1(5, pn1); EX2(pc0, 10, w1.y); KR1(9); SB();
;                     QK1(6, pn0); EX2(pc0, 12, w1.z); KR1(10); SB();
;                     QK1(7, pn1); EX2(pc0, 14, w1.w); KR1(11); SB();
;                     QK1(8, pn0); EX2(pc1, 0, w2.x); VR1(0); SB();
;                     QK1(9, pn1); EX2(pc1, 2, w2.y); VR1(1); SB();
;                     QK1(10, pn0); EX2(pc1, 4, w2.z); VR1(2); SB();
;                     QK1(11, pn1); EX2(pc1, 6, w2.w); VR1(3); SB();
;                 } else {
;                     KR1(0); KR1(1); KR1(2); KR1(3); SB();
;                     QK1(0, negm); EX2(pc0, 0, w0.x); EX2(pc0, 2, w0.y); KR1(4); SB();
;                     QK1(1, negm); EX2(pc0, 4, w0.z); EX2(pc0, 6, w0.w); KR1(5); SB();
;                     QK1(2, pn0); EX2(pc0, 8, w1.x); EX2(pc0, 10, w1.y); KR1(6); SB();
;                     QK1(3, pn1); EX2(pc0, 12, w1.z); EX2(pc0, 14, w1.w); KR1(7); SB();
;                     QK1(4, pn0); EX2(pc1, 0, w2.x); VR1(0); SB();
;                     QK1(5, pn1); EX2(pc1, 2, w2.y); VR1(1); SB();
;                     QK1(6, pn0); EX2(pc1, 4, w2.z); VR1(2); SB();
;                     QK1(7, pn1); EX2(pc1, 6, w2.w); VR1(3); SB();
;                 }
;                 PV1(0, w0); EX2(pc1, 8, w3.x); VR1(4); SB();
;                 PV1(1, w0); EX2(pc1, 10, w3.y); VR1(5); SB();
;                 PV1(2, w1); EX2(pc1, 12, w3.z); VR1(6); SB();
;                 PV1(3, w1); EX2(pc1, 14, w3.w); VR1(7); SB();
;                 lrun += sacc;
;                 PV1(4, w2); MASK_TILE(pn0, pn1, t + 1); SB();
;                 PV1(5, w2); SB();
;                 PV1(6, w3); SB();
;                 PV1(7, w3); rmn = rowmax32(pn0, pn1); if (!USE_NEGM) rmn -= mref; SB();
.Lmla_p17_go:
	v_exp_f32_e32 v222, v82
	v_exp_f32_e32 v223, v83
	v_add_f32_e32 v164, 0, v222
	v_cvt_pk_bf16_f32 v206, v222, v223
	v_add_f32_e32 v164, v223, v164
	v_exp_f32_e32 v224, v84
	v_exp_f32_e32 v225, v85
	v_add_f32_e32 v164, v224, v164
	v_cvt_pk_bf16_f32 v207, v224, v225
	v_add_f32_e32 v164, v225, v164
	s_waitcnt lgkmcnt(4)
	v_mfma_f32_32x32x16_bf16 v[34:49], v[182:185], v[114:117], v[66:81]
	ds_read_b128 v[198:201], v229 offset:13376
	v_exp_f32_e32 v222, v86
	v_exp_f32_e32 v223, v87
	v_add_f32_e32 v164, v222, v164
	v_cvt_pk_bf16_f32 v208, v222, v223
	v_add_f32_e32 v164, v223, v164
	s_waitcnt lgkmcnt(4)
	v_mfma_f32_32x32x16_bf16 v[50:65], v[186:189], v[114:117], v[66:81]
	ds_read_b128 v[182:185], v229 offset:20032
	v_exp_f32_e32 v224, v88
	v_exp_f32_e32 v225, v89
	v_add_f32_e32 v164, v224, v164
	v_cvt_pk_bf16_f32 v209, v224, v225
	v_add_f32_e32 v164, v225, v164
	s_waitcnt lgkmcnt(3)
	v_mfma_f32_32x32x16_bf16 v[34:49], v[190:193], v[118:121], v[34:49]
	ds_read_b128 v[186:189], v229 offset:13408
	v_exp_f32_e32 v222, v90
	v_exp_f32_e32 v223, v91
	v_add_f32_e32 v164, v222, v164
	v_cvt_pk_bf16_f32 v210, v222, v223
	v_add_f32_e32 v164, v223, v164
	s_waitcnt lgkmcnt(3)
	v_mfma_f32_32x32x16_bf16 v[50:65], v[194:197], v[118:121], v[50:65]
	ds_read_b128 v[190:193], v229 offset:20064
	v_exp_f32_e32 v224, v92
	v_exp_f32_e32 v225, v93
	v_add_f32_e32 v164, v224, v164
	v_cvt_pk_bf16_f32 v211, v224, v225
	v_add_f32_e32 v164, v225, v164
	s_waitcnt lgkmcnt(3)
	v_mfma_f32_32x32x16_bf16 v[34:49], v[198:201], v[122:125], v[34:49]
	ds_read_b128 v[194:197], v229 offset:13440
	v_exp_f32_e32 v222, v94
	v_exp_f32_e32 v223, v95
	v_add_f32_e32 v164, v222, v164
	v_cvt_pk_bf16_f32 v212, v222, v223
	v_add_f32_e32 v164, v223, v164
	s_waitcnt lgkmcnt(3)
	v_mfma_f32_32x32x16_bf16 v[50:65], v[182:185], v[122:125], v[50:65]
	ds_read_b128 v[198:201], v229 offset:20096
	v_exp_f32_e32 v224, v96
	v_exp_f32_e32 v225, v97
	v_add_f32_e32 v164, v224, v164
	v_cvt_pk_bf16_f32 v213, v224, v225
	v_add_f32_e32 v164, v225, v164
	s_waitcnt lgkmcnt(3)
	v_mfma_f32_32x32x16_bf16 v[34:49], v[186:189], v[126:129], v[34:49]
	ds_read_b128 v[182:185], v229 offset:13472
	v_exp_f32_e32 v222, v98
	v_exp_f32_e32 v223, v99
	v_add_f32_e32 v164, v222, v164
	v_cvt_pk_bf16_f32 v214, v222, v223
	v_add_f32_e32 v164, v223, v164
	s_waitcnt lgkmcnt(3)
	v_mfma_f32_32x32x16_bf16 v[50:65], v[190:193], v[126:129], v[50:65]
	ds_read_b128 v[186:189], v229 offset:20128
	v_exp_f32_e32 v224, v100
	v_exp_f32_e32 v225, v101
	v_add_f32_e32 v164, v224, v164
	v_cvt_pk_bf16_f32 v215, v224, v225
	v_add_f32_e32 v164, v225, v164
	s_waitcnt lgkmcnt(3)
	v_mfma_f32_32x32x16_bf16 v[34:49], v[194:197], v[130:133], v[34:49]
	ds_read_b128 v[190:193], v228 offset:35840
	v_exp_f32_e32 v222, v102
	v_exp_f32_e32 v223, v103
	v_add_f32_e32 v164, v222, v164
	v_cvt_pk_bf16_f32 v216, v222, v223
	v_add_f32_e32 v164, v223, v164
	s_waitcnt lgkmcnt(3)
	v_mfma_f32_32x32x16_bf16 v[50:65], v[198:201], v[130:133], v[50:65]
	ds_read_b128 v[194:197], v228 offset:40448
	v_exp_f32_e32 v224, v104
	v_exp_f32_e32 v225, v105
	v_add_f32_e32 v164, v224, v164
	v_cvt_pk_bf16_f32 v217, v224, v225
	v_add_f32_e32 v164, v225, v164
	s_waitcnt lgkmcnt(3)
	v_mfma_f32_32x32x16_bf16 v[34:49], v[182:185], v[134:137], v[34:49]
	ds_read_b128 v[198:201], v228 offset:35872
	v_exp_f32_e32 v222, v106
	v_exp_f32_e32 v223, v107
	v_add_f32_e32 v164, v222, v164
	v_cvt_pk_bf16_f32 v218, v222, v223
	v_add_f32_e32 v164, v223, v164
	s_waitcnt lgkmcnt(3)
	v_mfma_f32_32x32x16_bf16 v[50:65], v[186:189], v[134:137], v[50:65]
	ds_read_b128 v[182:185], v228 offset:40480
	v_exp_f32_e32 v224, v108
	v_exp_f32_e32 v225, v109
	v_add_f32_e32 v164, v224, v164
	v_cvt_pk_bf16_f32 v219, v224, v225
	v_add_f32_e32 v164, v225, v164
	s_waitcnt lgkmcnt(3)
	v_mfma_f32_32x32x16_bf16 v[2:17], v[190:193], v[206:209], v[2:17]
	ds_read_b128 v[186:189], v228 offset:35904
	v_exp_f32_e32 v222, v110
	v_exp_f32_e32 v223, v111
	v_add_f32_e32 v164, v222, v164
	v_cvt_pk_bf16_f32 v220, v222, v223
	v_add_f32_e32 v164, v223, v164
	s_mov_b32 s13, s20
	s_mov_b32 s20, s19
	s_add_i32 s19, s19, 1
	s_cmp_eq_u32 s19, s9
	s_cselect_b32 s19, 0, s19
	s_waitcnt lgkmcnt(3)
	v_mfma_f32_32x32x16_bf16 v[18:33], v[194:197], v[206:209], v[18:33]
	ds_read_b128 v[190:193], v228 offset:40512
	v_exp_f32_e32 v224, v112
	v_exp_f32_e32 v225, v113
	v_add_f32_e32 v164, v224, v164
	v_cvt_pk_bf16_f32 v221, v224, v225
	v_add_f32_e32 v164, v225, v164
	s_waitcnt vmcnt(2)
	ds_write_b128 v172, v[150:153] offset:22528
	v_lshl_add_u32 v222, s19, 17, v178
	global_load_dwordx4 v[150:153], v222, s[52:53]
	s_waitcnt lgkmcnt(4)
	v_mfma_f32_32x32x16_bf16 v[2:17], v[198:201], v[210:213], v[2:17]
	ds_read_b128 v[194:197], v228 offset:35936
	v_max3_f32 v224, v34, v35, v36
	v_max3_f32 v225, v50, v51, v52
	v_max3_f32 v224, v224, v37, v38
	v_max3_f32 v225, v225, v53, v54
	s_and_b64 vcc, exec, s[2:3]
	s_cbranch_vccz .Lmla_p17_nope
	ds_write_b128 v176, v[160:163] offset:22656
	v_lshl_add_u32 v222, s19, 12, v179
	global_load_dwordx4 v[160:163], v222, s[62:63]
.Lmla_p17_nope:
	s_waitcnt lgkmcnt(4)
	v_mfma_f32_32x32x16_bf16 v[18:33], v[182:185], v[210:213], v[18:33]
	ds_read_b128 v[198:201], v228 offset:40544
	ds_read_b128 v[182:185], v229 offset:26624
	v_max3_f32 v224, v224, v39, v40
	v_max3_f32 v225, v225, v55, v56
	v_max3_f32 v224, v224, v41, v42
	v_max3_f32 v225, v225, v57, v58
	v_add_u32_e32 v222, 0xb000, v173
	ds_write_b128 v222, v[202:205] offset:49152
	v_lshl_add_u32 v222, s13, 7, v168
	global_load_dwordx4 v[202:205], v222, s[56:57]
	s_waitcnt lgkmcnt(6)
	v_mfma_f32_32x32x16_bf16 v[2:17], v[186:189], v[214:217], v[2:17]
	ds_read_b128 v[186:189], v229 offset:33280
	v_max3_f32 v224, v224, v43, v44
	v_max3_f32 v225, v225, v59, v60
	v_max3_f32 v224, v224, v45, v46
	v_max3_f32 v225, v225, v61, v62
	s_waitcnt lgkmcnt(6)
	v_mfma_f32_32x32x16_bf16 v[18:33], v[190:193], v[214:217], v[18:33]
	ds_read_b128 v[190:193], v229 offset:26656
	v_max3_f32 v224, v224, v47, v48
	v_max3_f32 v225, v225, v63, v64
	v_max3_f32 v224, v224, v49, v65
	v_max_f32_e32 v224, v224, v225
	s_waitcnt lgkmcnt(5)
	v_mfma_f32_32x32x16_bf16 v[2:17], v[194:197], v[218:221], v[2:17]
	ds_read_b128 v[194:197], v229 offset:33312
	v_mov_b32_e32 v225, v224
	v_add_f32_e32 v1, v1, v164
	s_add_i32 s11, s11, 1
	v_permlane32_swap_b32_e32 v224, v225
	s_cmp_eq_u32 s9, s11
	v_max_f32_e32 v167, v224, v225
	v_cmp_lt_f32_e32 vcc, s66, v167
	s_waitcnt lgkmcnt(5)
	v_mfma_f32_32x32x16_bf16 v[18:33], v[198:201], v[218:221], v[18:33]
	s_waitcnt lgkmcnt(3)
	s_barrier

; #define SB() __builtin_amdgcn_sched_barrier(0)
; template <int VAR>
; __device__ __forceinline__ void attn_phase(LAS unsigned char* lds, const AttnP P, int vcu, int G, int wave_s) {
;     ...
;                 if (ND0 == 6) {
;                     KR1(0); KR1(1); KR1(2); KR1(3); SB();
;                     QK1(0, negm); EX2(pc0, 0, w0.x); KR1(4); SB();
;                     QK1(1, negm); EX2(pc0, 2, w0.y); KR1(5); SB();
;                     QK1(2, pn0); EX2(pc0, 4, w0.z); KR1(6); SB();
;                     QK1(3, pn1); EX2(pc0, 6, w0.w); KR1(7); SB();
;                     QK1(4, pn0); EX2(pc0, 8, w1.x); KR1(8); SB();
;                     QK1(5, pn1); EX2(pc0, 10, w1.y); KR1(9); SB();
;                     QK1(6, pn0); EX2(pc0, 12, w1.z); KR1(10); SB();
;                     QK1(7, pn1); EX2(pc0, 14, w1.w); KR1(11); SB();
;                     QK1(8, pn0); EX2(pc1, 0, w2.x); VR1(0); SB();
;                     QK1(9, pn1); EX2(pc1, 2, w2.y); VR1(1); SB();
;                     QK1(10, pn0); EX2(pc1, 4, w2.z); VR1(2); SB();
;                     QK1(11, pn1); EX2(pc1, 6, w2.w); VR1(3); SB();
;                 } else {
;                     KR1(0); KR1(1); KR1(2); KR1(3); SB();
;                     QK1(0, negm); EX2(pc0, 0, w0.x); EX2(pc0, 2, w0.y); KR1(4); SB();
;                     QK1(1, negm); EX2(pc0, 4, w0.z); EX2(pc0, 6, w0.w); KR1(5); SB();
;                     QK1(2, pn0); EX2(pc0, 8, w1.x); EX2(pc0, 10, w1.y); KR1(6); SB();
;                     QK1(3, pn1); EX2(pc0, 12, w1.z); EX2(pc0, 14, w1.w); KR1(7); SB();
;                     QK1(4, pn0); EX2(pc1, 0, w2.x); VR1(0); SB();
;                     QK1(5, pn1); EX2(pc1, 2, w2.y); VR1(1); SB();
;                     QK1(6, pn0); EX2(pc1, 4, w2.z); VR1(2); SB();
;                     QK1(7, pn1); EX2(pc1, 6, w2.w); VR1(3); SB();
;                 }
;                 PV1(0, w0); EX2(pc1, 8, w3.x); VR1(4); SB();
;                 PV1(1, w0); EX2(pc1, 10, w3.y); VR1(5); SB();
;                 PV1(2, w1); EX2(pc1, 12, w3.z); VR1(6); SB();
;                 PV1(3, w1); EX2(pc1, 14, w3.w); VR1(7); SB();
;                 lrun += sacc;
;                 PV1(4, w2); MASK_TILE(pn0, pn1, t + 1); SB();
;                 PV1(5, w2); SB();
;                 PV1(6, w3); SB();
;                 PV1(7, w3); rmn = rowmax32(pn0, pn1); if (!USE_NEGM) rmn -= mref; SB();
.Lmla_p19_go:
	v_exp_f32_e32 v222, v82
	v_exp_f32_e32 v223, v83
	v_add_f32_e32 v164, 0, v222
	v_cvt_pk_bf16_f32 v206, v222, v223
	v_add_f32_e32 v164, v223, v164
	v_exp_f32_e32 v224, v84
	v_exp_f32_e32 v225, v85
	v_add_f32_e32 v164, v224, v164
	v_cvt_pk_bf16_f32 v207, v224, v225
	v_add_f32_e32 v164, v225, v164
	s_waitcnt lgkmcnt(4)
	v_mfma_f32_32x32x16_bf16 v[34:49], v[182:185], v[114:117], v[66:81]
	ds_read_b128 v[198:201], v174 offset:64
	v_exp_f32_e32 v222, v86
	v_exp_f32_e32 v223, v87
	v_add_f32_e32 v164, v222, v164
	v_cvt_pk_bf16_f32 v208, v222, v223
	v_add_f32_e32 v164, v223, v164
	s_waitcnt lgkmcnt(4)
	v_mfma_f32_32x32x16_bf16 v[50:65], v[186:189], v[114:117], v[66:81]
	ds_read_b128 v[182:185], v174 offset:6720
	v_exp_f32_e32 v224, v88
	v_exp_f32_e32 v225, v89
	v_add_f32_e32 v164, v224, v164
	v_cvt_pk_bf16_f32 v209, v224, v225
	v_add_f32_e32 v164, v225, v164
	s_waitcnt lgkmcnt(3)
	v_mfma_f32_32x32x16_bf16 v[34:49], v[190:193], v[118:121], v[34:49]
	ds_read_b128 v[186:189], v174 offset:96
	v_exp_f32_e32 v222, v90
	v_exp_f32_e32 v223, v91
	v_add_f32_e32 v164, v222, v164
	v_cvt_pk_bf16_f32 v210, v222, v223
	v_add_f32_e32 v164, v223, v164
	s_waitcnt lgkmcnt(3)
	v_mfma_f32_32x32x16_bf16 v[50:65], v[194:197], v[118:121], v[50:65]
	ds_read_b128 v[190:193], v174 offset:6752
	v_exp_f32_e32 v224, v92
	v_exp_f32_e32 v225, v93
	v_add_f32_e32 v164, v224, v164
	v_cvt_pk_bf16_f32 v211, v224, v225
	v_add_f32_e32 v164, v225, v164
	s_waitcnt lgkmcnt(3)
	v_mfma_f32_32x32x16_bf16 v[34:49], v[198:201], v[122:125], v[34:49]
	ds_read_b128 v[194:197], v174 offset:128
	v_exp_f32_e32 v222, v94
	v_exp_f32_e32 v223, v95
	v_add_f32_e32 v164, v222, v164
	v_cvt_pk_bf16_f32 v212, v222, v223
	v_add_f32_e32 v164, v223, v164
	s_waitcnt lgkmcnt(3)
	v_mfma_f32_32x32x16_bf16 v[50:65], v[182:185], v[122:125], v[50:65]
	ds_read_b128 v[198:201], v174 offset:6784
	v_exp_f32_e32 v224, v96
	v_exp_f32_e32 v225, v97
	v_add_f32_e32 v164, v224, v164
	v_cvt_pk_bf16_f32 v213, v224, v225
	v_add_f32_e32 v164, v225, v164
	s_waitcnt lgkmcnt(3)
	v_mfma_f32_32x32x16_bf16 v[34:49], v[186:189], v[126:129], v[34:49]
	ds_read_b128 v[182:185], v174 offset:160
	v_exp_f32_e32 v222, v98
	v_exp_f32_e32 v223, v99
	v_add_f32_e32 v164, v222, v164
	v_cvt_pk_bf16_f32 v214, v222, v223
	v_add_f32_e32 v164, v223, v164
	s_waitcnt lgkmcnt(3)
	v_mfma_f32_32x32x16_bf16 v[50:65], v[190:193], v[126:129], v[50:65]
	ds_read_b128 v[186:189], v174 offset:6816
	v_exp_f32_e32 v224, v100
	v_exp_f32_e32 v225, v101
	v_add_f32_e32 v164, v224, v164
	v_cvt_pk_bf16_f32 v215, v224, v225
	v_add_f32_e32 v164, v225, v164
	s_waitcnt lgkmcnt(3)
	v_mfma_f32_32x32x16_bf16 v[34:49], v[194:197], v[130:133], v[34:49]
	ds_read_b128 v[190:193], v181 offset:49152
	v_exp_f32_e32 v222, v102
	v_exp_f32_e32 v223, v103
	v_add_f32_e32 v164, v222, v164
	v_cvt_pk_bf16_f32 v216, v222, v223
	v_add_f32_e32 v164, v223, v164
	s_waitcnt lgkmcnt(3)
	v_mfma_f32_32x32x16_bf16 v[50:65], v[198:201], v[130:133], v[50:65]
	ds_read_b128 v[194:197], v181 offset:53760
	v_exp_f32_e32 v224, v104
	v_exp_f32_e32 v225, v105
	v_add_f32_e32 v164, v224, v164
	v_cvt_pk_bf16_f32 v217, v224, v225
	v_add_f32_e32 v164, v225, v164
	s_waitcnt lgkmcnt(3)
	v_mfma_f32_32x32x16_bf16 v[34:49], v[182:185], v[134:137], v[34:49]
	ds_read_b128 v[198:201], v181 offset:49184
	v_exp_f32_e32 v222, v106
	v_exp_f32_e32 v223, v107
	v_add_f32_e32 v164, v222, v164
	v_cvt_pk_bf16_f32 v218, v222, v223
	v_add_f32_e32 v164, v223, v164
	s_waitcnt lgkmcnt(3)
	v_mfma_f32_32x32x16_bf16 v[50:65], v[186:189], v[134:137], v[50:65]
	ds_read_b128 v[182:185], v181 offset:53792
	v_exp_f32_e32 v224, v108
	v_exp_f32_e32 v225, v109
	v_add_f32_e32 v164, v224, v164
	v_cvt_pk_bf16_f32 v219, v224, v225
	v_add_f32_e32 v164, v225, v164
	s_waitcnt lgkmcnt(3)
	v_mfma_f32_32x32x16_bf16 v[2:17], v[190:193], v[206:209], v[2:17]
	ds_read_b128 v[186:189], v181 offset:49216
	v_exp_f32_e32 v222, v110
	v_exp_f32_e32 v223, v111
	v_add_f32_e32 v164, v222, v164
	v_cvt_pk_bf16_f32 v220, v222, v223
	v_add_f32_e32 v164, v223, v164
	s_mov_b32 s13, s20
	s_mov_b32 s20, s19
	s_add_i32 s19, s19, 1
	s_cmp_eq_u32 s19, s9
	s_cselect_b32 s19, 0, s19
	s_waitcnt lgkmcnt(3)
	v_mfma_f32_32x32x16_bf16 v[18:33], v[194:197], v[206:209], v[18:33]
	ds_read_b128 v[190:193], v181 offset:53824
	v_exp_f32_e32 v224, v112
	v_exp_f32_e32 v225, v113
	v_add_f32_e32 v164, v224, v164
	v_cvt_pk_bf16_f32 v221, v224, v225
	v_add_f32_e32 v164, v225, v164
	s_waitcnt vmcnt(2)
	ds_write_b128 v172, v[150:153] offset:58368
	v_lshl_add_u32 v222, s19, 17, v178
	global_load_dwordx4 v[150:153], v222, s[52:53]
	s_waitcnt lgkmcnt(4)
	v_mfma_f32_32x32x16_bf16 v[2:17], v[198:201], v[210:213], v[2:17]
	ds_read_b128 v[194:197], v181 offset:49248
	v_max3_f32 v224, v34, v35, v36
	v_max3_f32 v225, v50, v51, v52
	v_max3_f32 v224, v224, v37, v38
	v_max3_f32 v225, v225, v53, v54
	s_and_b64 vcc, exec, s[2:3]
	s_cbranch_vccz .Lmla_p19_nope
	ds_write_b128 v176, v[160:163] offset:58496
	v_lshl_add_u32 v222, s19, 12, v179
	global_load_dwordx4 v[160:163], v222, s[62:63]
.Lmla_p19_nope:
	s_waitcnt lgkmcnt(4)
	v_mfma_f32_32x32x16_bf16 v[18:33], v[182:185], v[210:213], v[18:33]
	ds_read_b128 v[198:201], v181 offset:53856
	ds_read_b128 v[182:185], v174 offset:22528
	v_max3_f32 v224, v224, v39, v40
	v_max3_f32 v225, v225, v55, v56
	v_max3_f32 v224, v224, v41, v42
	v_max3_f32 v225, v225, v57, v58
	ds_write_b128 v173, v[202:205] offset:35840
	v_lshl_add_u32 v222, s13, 7, v168
	global_load_dwordx4 v[202:205], v222, s[56:57]
	s_waitcnt lgkmcnt(6)
	v_mfma_f32_32x32x16_bf16 v[2:17], v[186:189], v[214:217], v[2:17]
	ds_read_b128 v[186:189], v174 offset:29184
	v_max3_f32 v224, v224, v43, v44
	v_max3_f32 v225, v225, v59, v60
	v_max3_f32 v224, v224, v45, v46
	v_max3_f32 v225, v225, v61, v62
	s_waitcnt lgkmcnt(6)
	v_mfma_f32_32x32x16_bf16 v[18:33], v[190:193], v[214:217], v[18:33]
	ds_read_b128 v[190:193], v174 offset:22560
	v_max3_f32 v224, v224, v47, v48
	v_max3_f32 v225, v225, v63, v64
	v_max3_f32 v224, v224, v49, v65
	v_max_f32_e32 v224, v224, v225
	s_waitcnt lgkmcnt(5)
	v_mfma_f32_32x32x16_bf16 v[2:17], v[194:197], v[218:221], v[2:17]
	ds_read_b128 v[194:197], v174 offset:29216
	v_mov_b32_e32 v225, v224
	v_add_f32_e32 v1, v1, v164
	s_add_i32 s11, s11, 1
	v_permlane32_swap_b32_e32 v224, v225
	s_cmp_eq_u32 s9, s11
	v_max_f32_e32 v167, v224, v225
	v_cmp_lt_f32_e32 vcc, s66, v167
	s_waitcnt lgkmcnt(5)
	v_mfma_f32_32x32x16_bf16 v[18:33], v[198:201], v[218:221], v[18:33]
	s_waitcnt lgkmcnt(3)
	s_barrier
	s_branch .Lmla_p0
